# v28 + attention O stores transposed through LDS into full-line write-through 16B stores
# speedup vs baseline: 1.0079x; 1.0079x over previous
.LBB0_810:
	s_or_b64 exec, exec, s[66:67]
	s_add_i32 s7, s6, 1
	v_cvt_f32_i32_e32 v1, s7
	s_mov_b32 s7, 0xc2fc0000
	v_readlane_b32 s40, v253, 24
	v_readlane_b32 s50, v253, 34
	v_mul_f32_e32 v2, -0.5, v1
	v_cmp_gt_f32_e32 vcc, s7, v2
	s_and_b64 s[12:13], vcc, exec
	s_cselect_b32 s7, 0xffffffc0, 0
	v_cndmask_b32_e32 v2, 0, v247, vcc
	v_fmac_f32_e32 v2, -0.5, v1
	v_exp_f32_e32 v1, v2
	v_readlane_b32 s51, v253, 35
	s_waitcnt lgkmcnt(0)
	s_barrier
	v_ldexp_f32 v2, v1, s7
	v_readlane_b32 s7, v255, 15
	s_add_i32 s6, s6, s7
	s_ashr_i32 s7, s6, 31
	s_lshl_b64 s[6:7], s[6:7], 2
	s_add_u32 s6, s50, s6
	s_addc_u32 s7, s51, s7
	global_load_dword v55, v0, s[6:7]
	ds_read_b128 v[56:59], v156
	ds_read_b128 v[60:63], v156 offset:64
	s_cmp_eq_u32 s22, 0
	v_mul_f32_e32 v52, 0xbfb8aa3b, v2
	s_waitcnt lgkmcnt(1)
	v_mfma_f32_16x16x32_bf16 v[56:59], v[56:59], v[48:51], 0
	v_lshl_add_u64 v[2:3], s[68:69], 1, v[68:69]
	v_readlane_b32 s100, v253, 48
	v_and_b32_e32 v224, 7, v207
	v_lshrrev_b32_e32 v225, 4, v207
	s_mul_i32 s100, s100, 0x900
	v_lshlrev_b32_e32 v224, 4, v224
	v_lshlrev_b32_e32 v221, 3, v225
	v_mul_u32_u24_e32 v220, 0x90, v84
	v_sub_u32_e32 v222, v224, v221
	v_add_u32_e32 v220, v220, v221
	v_lshrrev_b32_e32 v225, 3, v207
	v_add_u32_e32 v220, s100, v220
	v_mul_u32_u24_e32 v221, 0x90, v225
	v_add_u32_e32 v220, 0xd000, v220
	v_add_u32_e32 v221, v221, v224
	v_add_u32_e32 v225, s2, v225
	v_add_u32_e32 v221, s100, v221
	v_lshl_add_u32 v224, v225, 11, v222
	v_add_u32_e32 v221, 0xd000, v221
	v_mov_b32_e32 v225, 0
	v_lshl_add_u64 v[222:223], v[2:3], 0, v[224:225]
	s_cselect_b64 s[68:69], -1, 0
	v_cndmask_b32_e64 v53, v240, v96, s[68:69]
	s_waitcnt lgkmcnt(0)
	v_mfma_f32_16x16x32_bf16 v[60:63], v[60:63], v[44:47], v[56:59]
	v_add_f32_e32 v54, -1.0, v53
	ds_read_b128 v[80:83], v156 offset:2368
	v_add_f32_e32 v163, 0xc2400000, v53
	v_add_f32_e32 v56, -2.0, v53
	s_cmp_gt_u32 s22, 64
	s_nop 2
	v_fma_f32 v57, v52, |v56|, v62
	v_add_f32_e32 v56, 0xc0400000, v53
	v_fma_f32 v59, v52, v53, v60
	v_fma_f32 v58, v52, |v54|, v61
	v_fma_f32 v56, v52, |v56|, v63
	ds_read_b128 v[60:63], v156 offset:2304
	s_waitcnt lgkmcnt(0)
	v_mfma_f32_16x16x32_bf16 v[60:63], v[60:63], v[48:51], 0
	ds_read_b128 v[164:167], v156 offset:4672
	s_cselect_b64 s[66:67], -1, 0
	s_cmpk_gt_u32 s22, 0x50
	v_mfma_f32_16x16x32_bf16 v[80:83], v[80:83], v[44:47], v[60:63]
	s_cselect_b64 s[70:71], -1, 0
	s_cmpk_gt_u32 s22, 0x60
	s_cselect_b64 s[72:73], -1, 0
	s_nop 0
	v_add_f32_e32 v60, 0xc1800000, v53
	s_cmpk_gt_u32 s22, 0x70
	s_nop 1
	v_fma_f32 v63, v52, |v60|, v80
	v_add_f32_e32 v60, 0xc1880000, v53
	v_fma_f32 v62, v52, |v60|, v81
	v_add_f32_e32 v60, 0xc1900000, v53
	v_fma_f32 v61, v52, |v60|, v82
	v_add_f32_e32 v60, 0xc1980000, v53
	v_fma_f32 v60, v52, |v60|, v83
	ds_read_b128 v[80:83], v156 offset:4608
	s_waitcnt lgkmcnt(0)
	v_mfma_f32_16x16x32_bf16 v[80:83], v[80:83], v[48:51], 0
	ds_read_b128 v[168:171], v157 offset:64
	s_cselect_b64 s[74:75], -1, 0
	ds_read_b128 v[196:199], v156 offset:23040
	ds_read_b128 v[200:203], v156 offset:23104
	v_mfma_f32_16x16x32_bf16 v[164:167], v[164:167], v[44:47], v[80:83]
	s_mov_b32 s12, 0x3fb8aa3b
	s_and_b32 s2, s2, 0x7fffffe0
	v_readlane_b32 s41, v253, 25
	v_add_f32_e32 v80, 0xc2000000, v53
	s_waitcnt lgkmcnt(1)
	v_mfma_f32_16x16x32_bf16 v[196:199], v[196:199], v[48:51], 0
	s_nop 1
	v_fma_f32 v83, v52, |v80|, v164
	v_add_f32_e32 v80, 0xc2040000, v53
	v_fma_f32 v82, v52, |v80|, v165
	v_add_f32_e32 v80, 0xc2080000, v53
	v_fma_f32 v81, v52, |v80|, v166
	v_add_f32_e32 v80, 0xc20c0000, v53
	v_fma_f32 v80, v52, |v80|, v167
	ds_read_b128 v[164:167], v157
	s_waitcnt lgkmcnt(0)
	v_mfma_f32_16x16x32_bf16 v[164:167], v[164:167], v[48:51], 0
	ds_read_b128 v[172:175], v156 offset:9280
	s_waitcnt vmcnt(0)
	v_mul_f32_e32 v1, 0x3fb8aa3b, v55
	v_max3_f32 v54, v1, v59, v58
	v_mfma_f32_16x16x32_bf16 v[166:169], v[168:171], v[44:47], v[164:167]
	v_max3_f32 v54, v54, v57, v56
	v_max3_f32 v54, v54, v63, v62
	v_max3_f32 v54, v54, v61, v60
	v_max3_f32 v54, v54, v83, v82
	v_max3_f32 v54, v54, v81, v80
	s_nop 2
	v_fma_f32 v166, v52, |v163|, v166
	v_add_f32_e32 v163, 0xc2440000, v53
	v_fma_f32 v165, v52, |v163|, v167
	v_add_f32_e32 v163, 0xc2480000, v53
	v_add_f32_e32 v53, 0xc24c0000, v53
	v_fma_f32 v164, v52, |v163|, v168
	v_fma_f32 v163, v52, |v53|, v169
	ds_read_b128 v[168:171], v156 offset:9216
	s_waitcnt lgkmcnt(0)
	v_mfma_f32_16x16x32_bf16 v[168:171], v[168:171], v[48:51], 0
	v_max3_f32 v54, v54, v166, v165
	v_max3_f32 v53, v54, v164, v163
	v_cndmask_b32_e64 v54, v96, v240, s[66:67]
	v_mfma_f32_16x16x32_bf16 v[170:173], v[172:175], v[44:47], v[168:171]
	v_add_f32_e32 v167, 0xc2800000, v54
	ds_read_b128 v[176:179], v156 offset:11584
	ds_read_b128 v[180:183], v156 offset:13888
	v_mfma_f32_16x16x32_bf16 v[196:199], v[200:203], v[44:47], v[196:199]
	v_readlane_b32 s42, v253, 26
	s_nop 2
	v_fma_f32 v170, v52, |v167|, v170
	v_add_f32_e32 v167, 0xc2820000, v54
	v_fma_f32 v169, v52, |v167|, v171
	v_add_f32_e32 v167, 0xc2840000, v54
	v_add_f32_e32 v54, 0xc2860000, v54
	v_fma_f32 v168, v52, |v167|, v172
	v_fma_f32 v167, v52, |v54|, v173
	ds_read_b128 v[172:175], v156 offset:11520
	s_waitcnt lgkmcnt(0)
	v_mfma_f32_16x16x32_bf16 v[172:175], v[172:175], v[48:51], 0
	v_cndmask_b32_e64 v54, v96, v240, s[70:71]
	v_add_f32_e32 v171, 0xc2a00000, v54
	ds_read_b128 v[184:187], v158 offset:64
	v_mfma_f32_16x16x32_bf16 v[174:177], v[176:179], v[44:47], v[172:175]
	v_max3_f32 v53, v53, v170, v169
	v_max3_f32 v53, v53, v168, v167
	v_readlane_b32 s43, v253, 27
	ds_read_b128 v[188:191], v156 offset:18496
	v_readlane_b32 s44, v253, 28
	s_nop 2
	v_fma_f32 v174, v52, |v171|, v174
	v_add_f32_e32 v171, 0xc2a20000, v54
	v_fma_f32 v173, v52, |v171|, v175
	v_add_f32_e32 v171, 0xc2a40000, v54
	v_add_f32_e32 v54, 0xc2a60000, v54
	v_fma_f32 v172, v52, |v171|, v176
	v_fma_f32 v171, v52, |v54|, v177
	ds_read_b128 v[176:179], v156 offset:13824
	s_waitcnt lgkmcnt(0)
	v_mfma_f32_16x16x32_bf16 v[176:179], v[176:179], v[48:51], 0
	v_cndmask_b32_e64 v54, v96, v240, s[72:73]
	v_add_f32_e32 v175, 0xc2c00000, v54
	ds_read_b128 v[192:195], v156 offset:20800
	v_mfma_f32_16x16x32_bf16 v[178:181], v[180:183], v[44:47], v[176:179]
	v_max3_f32 v53, v53, v174, v173
	v_max3_f32 v53, v53, v172, v171
	v_readlane_b32 s45, v253, 29
	v_readlane_b32 s46, v253, 30
	v_readlane_b32 s47, v253, 31
	s_nop 2
	v_fma_f32 v178, v52, |v175|, v178
	v_add_f32_e32 v175, 0xc2c20000, v54
	v_fma_f32 v177, v52, |v175|, v179
	v_add_f32_e32 v175, 0xc2c40000, v54
	v_add_f32_e32 v54, 0xc2c60000, v54
	v_fma_f32 v176, v52, |v175|, v180
	v_fma_f32 v175, v52, |v54|, v181
	ds_read_b128 v[180:183], v158
	s_waitcnt lgkmcnt(0)
	v_mfma_f32_16x16x32_bf16 v[180:183], v[180:183], v[48:51], 0
	v_cndmask_b32_e64 v54, v96, v240, s[74:75]
	v_add_f32_e32 v179, 0xc2e00000, v54
	v_max3_f32 v53, v53, v178, v177
	v_mfma_f32_16x16x32_bf16 v[182:185], v[184:187], v[44:47], v[180:183]
	v_max3_f32 v53, v53, v176, v175
	v_readlane_b32 s48, v253, 32
	v_readlane_b32 s49, v253, 33
	v_readlane_b32 s52, v253, 36
	v_readlane_b32 s53, v253, 37
	s_nop 2
	v_fma_f32 v182, v52, |v179|, v182
	v_add_f32_e32 v179, 0xc2e20000, v54
	v_fma_f32 v181, v52, |v179|, v183
	v_add_f32_e32 v179, 0xc2e40000, v54
	v_add_f32_e32 v54, 0xc2e60000, v54
	v_fma_f32 v180, v52, |v179|, v184
	v_fma_f32 v179, v52, |v54|, v185
	ds_read_b128 v[184:187], v156 offset:18432
	s_waitcnt lgkmcnt(0)
	v_mfma_f32_16x16x32_bf16 v[184:187], v[184:187], v[48:51], 0
	v_cndmask_b32_e64 v54, v240, v96, s[76:77]
	v_max3_f32 v53, v53, v182, v181
	v_max3_f32 v53, v53, v180, v179
	v_mfma_f32_16x16x32_bf16 v[188:191], v[188:191], v[44:47], v[184:187]
	v_readlane_b32 s54, v253, 38
	v_readlane_b32 s55, v253, 39
	s_nop 1
	v_add_f32_e32 v185, 0xc3200000, v54
	v_fma_f32 v201, v52, |v185|, v196
	v_add_f32_e32 v185, 0xc3210000, v54
	v_fma_f32 v202, v52, |v185|, v197
	v_add_f32_e32 v185, 0xc3220000, v54
	v_fma_f32 v203, v52, |v185|, v198
	v_add_f32_e32 v185, 0xc3230000, v54
	v_fma_f32 v187, v52, |v100|, v188
	v_fma_f32 v186, v52, |v101|, v189
	v_fma_f32 v184, v52, |v102|, v190
	v_fma_f32 v183, v52, |v103|, v191
	ds_read_b128 v[188:191], v156 offset:20736
	v_fma_f32 v204, v52, |v185|, v199
	ds_read_b128 v[196:199], v159
	s_waitcnt lgkmcnt(1)
	v_mfma_f32_16x16x32_bf16 v[188:191], v[188:191], v[48:51], 0
	v_max3_f32 v53, v53, v187, v186
	v_max3_f32 v53, v53, v184, v183
	s_waitcnt lgkmcnt(0)
	v_mfma_f32_16x16x32_bf16 v[48:51], v[196:199], v[48:51], 0
	ds_read_b128 v[196:199], v159 offset:64
	v_mfma_f32_16x16x32_bf16 v[188:191], v[192:195], v[44:47], v[188:191]
	s_waitcnt lgkmcnt(0)
	v_mfma_f32_16x16x32_bf16 v[44:47], v[196:199], v[44:47], v[48:51]
	s_nop 3
	v_add_f32_e32 v48, 0xc3300000, v54
	s_nop 0
	v_fma_f32 v195, v52, |v104|, v188
	v_fma_f32 v193, v52, |v105|, v189
	v_max3_f32 v53, v53, v195, v193
	v_fma_f32 v192, v52, |v106|, v190
	v_fma_f32 v191, v52, |v107|, v191
	v_max3_f32 v53, v53, v192, v191
	v_max3_f32 v53, v53, v201, v202
	v_fma_f32 v44, v52, |v48|, v44
	v_add_f32_e32 v48, 0xc3310000, v54
	v_add_f32_e32 v49, 0xc3320000, v54
	v_max3_f32 v53, v53, v203, v204
	v_fma_f32 v45, v52, |v48|, v45
	v_fma_f32 v49, v52, |v49|, v46
	v_add_f32_e32 v46, 0xc3330000, v54
	v_max3_f32 v48, v53, v44, v45
	v_fma_f32 v50, v52, |v46|, v47
	v_max3_f32 v46, v48, v49, v50
	v_and_b32_e32 v48, 64, v236
	v_xor_b32_e32 v47, 16, v236
	v_add_u32_e32 v48, 64, v48
	v_cmp_lt_i32_e32 vcc, v47, v48
	s_nop 1
	v_cndmask_b32_e32 v47, v236, v47, vcc
	v_lshlrev_b32_e32 v53, 2, v47
	ds_bpermute_b32 v47, v53, v46
	s_waitcnt lgkmcnt(0)
	v_max_f32_e32 v47, v47, v47
	v_max_f32_e32 v46, v46, v47
	v_xor_b32_e32 v47, 32, v236
	v_cmp_lt_i32_e32 vcc, v47, v48
	s_nop 1
	v_cndmask_b32_e32 v47, v236, v47, vcc
	v_lshlrev_b32_e32 v54, 2, v47
	ds_bpermute_b32 v47, v54, v46
	s_waitcnt lgkmcnt(0)
	v_max_f32_e32 v47, v47, v47
	v_max_f32_e32 v48, v46, v47
	v_sub_f32_e32 v46, v59, v48
	v_exp_f32_e32 v51, v46
	v_sub_f32_e32 v47, v58, v48
	v_exp_f32_e32 v205, v47
	v_sub_f32_e32 v47, v57, v48
	v_exp_f32_e32 v208, v47
	v_sub_f32_e32 v47, v56, v48
	v_exp_f32_e32 v209, v47
	v_sub_f32_e32 v47, v63, v48
	v_add_f32_e32 v46, 0, v51
	v_exp_f32_e32 v210, v47
	v_sub_f32_e32 v47, v62, v48
	v_add_f32_e32 v46, v205, v46
	v_exp_f32_e32 v211, v47
	v_sub_f32_e32 v47, v61, v48
	v_add_f32_e32 v46, v208, v46
	v_exp_f32_e32 v212, v47
	v_sub_f32_e32 v47, v60, v48
	v_add_f32_e32 v46, v209, v46
	v_exp_f32_e32 v213, v47
	v_sub_f32_e32 v47, v83, v48
	v_add_f32_e32 v46, v210, v46
	v_exp_f32_e32 v197, v47
	v_sub_f32_e32 v47, v82, v48
	v_add_f32_e32 v46, v211, v46
	v_exp_f32_e32 v198, v47
	v_sub_f32_e32 v47, v81, v48
	v_add_f32_e32 v46, v212, v46
	v_exp_f32_e32 v199, v47
	v_sub_f32_e32 v47, v80, v48
	v_add_f32_e32 v46, v213, v46
	v_exp_f32_e32 v200, v47
	v_sub_f32_e32 v47, v166, v48
	v_add_f32_e32 v46, v197, v46
	v_exp_f32_e32 v216, v47
	v_sub_f32_e32 v47, v165, v48
	v_add_f32_e32 v46, v198, v46
	v_exp_f32_e32 v217, v47
	v_sub_f32_e32 v47, v164, v48
	v_add_f32_e32 v46, v199, v46
	v_exp_f32_e32 v218, v47
	v_sub_f32_e32 v47, v163, v48
	v_add_f32_e32 v46, v200, v46
	v_exp_f32_e32 v219, v47
	v_sub_f32_e32 v47, v170, v48
	v_add_f32_e32 v46, v216, v46
	v_exp_f32_e32 v185, v47
	v_sub_f32_e32 v47, v169, v48
	v_add_f32_e32 v46, v217, v46
	v_exp_f32_e32 v188, v47
	v_sub_f32_e32 v47, v168, v48
	v_add_f32_e32 v46, v218, v46
	v_exp_f32_e32 v189, v47
	v_sub_f32_e32 v47, v167, v48
	v_add_f32_e32 v46, v219, v46
	v_exp_f32_e32 v190, v47
	v_sub_f32_e32 v47, v174, v48
	v_add_f32_e32 v46, v185, v46
	v_exp_f32_e32 v174, v47
	v_sub_f32_e32 v47, v173, v48
	v_add_f32_e32 v46, v188, v46
	v_exp_f32_e32 v173, v47
	v_sub_f32_e32 v47, v172, v48
	v_add_f32_e32 v46, v189, v46
	v_exp_f32_e32 v194, v47
	v_sub_f32_e32 v47, v171, v48
	v_add_f32_e32 v46, v190, v46
	v_exp_f32_e32 v196, v47
	v_sub_f32_e32 v47, v178, v48
	v_add_f32_e32 v46, v174, v46
	v_exp_f32_e32 v165, v47
	v_sub_f32_e32 v47, v177, v48
	v_add_f32_e32 v46, v173, v46
	v_exp_f32_e32 v166, v47
	v_sub_f32_e32 v47, v176, v48
	v_add_f32_e32 v46, v194, v46
	v_exp_f32_e32 v167, v47
	v_sub_f32_e32 v47, v175, v48
	v_add_f32_e32 v46, v196, v46
	v_exp_f32_e32 v168, v47
	v_sub_f32_e32 v47, v182, v48
	v_add_f32_e32 v46, v165, v46
	v_exp_f32_e32 v169, v47
	v_sub_f32_e32 v47, v181, v48
	v_add_f32_e32 v46, v166, v46
	v_exp_f32_e32 v170, v47
	v_sub_f32_e32 v47, v180, v48
	v_add_f32_e32 v46, v167, v46
	v_exp_f32_e32 v171, v47
	v_sub_f32_e32 v47, v179, v48
	v_add_f32_e32 v46, v168, v46
	v_exp_f32_e32 v172, v47
	v_sub_f32_e32 v47, v187, v48
	v_add_f32_e32 v46, v169, v46
	v_exp_f32_e32 v62, v47
	v_sub_f32_e32 v47, v186, v48
	v_add_f32_e32 v46, v170, v46
	v_exp_f32_e32 v63, v47
	v_sub_f32_e32 v47, v184, v48
	v_add_f32_e32 v46, v171, v46
	v_exp_f32_e32 v80, v47
	v_sub_f32_e32 v47, v183, v48
	v_add_f32_e32 v46, v172, v46
	v_exp_f32_e32 v81, v47
	v_sub_f32_e32 v47, v195, v48
	v_add_f32_e32 v46, v62, v46
	v_exp_f32_e32 v82, v47
	v_sub_f32_e32 v47, v193, v48
	v_add_f32_e32 v46, v63, v46
	v_exp_f32_e32 v83, v47
	v_sub_f32_e32 v47, v192, v48
	v_add_f32_e32 v46, v80, v46
	v_exp_f32_e32 v163, v47
	v_sub_f32_e32 v47, v191, v48
	v_add_f32_e32 v46, v81, v46
	v_exp_f32_e32 v164, v47
	v_add_f32_e32 v46, v82, v46
	v_add_f32_e32 v46, v83, v46
	v_add_f32_e32 v46, v163, v46
	v_add_f32_e32 v47, v164, v46
	v_sub_f32_e32 v46, v201, v48
	v_exp_f32_e32 v46, v46
	v_sub_f32_e32 v44, v44, v48
	v_sub_f32_e32 v45, v45, v48
	v_cvt_pk_bf16_f32 v176, v51, v205
	v_add_f32_e32 v56, v46, v47
	v_sub_f32_e32 v47, v202, v48
	v_exp_f32_e32 v47, v47
	v_add_u32_e32 v51, 0x6800, v160
	v_cvt_pk_bf16_f32 v177, v208, v209
	v_cvt_pk_bf16_f32 v178, v210, v211
	v_add_f32_e32 v57, v47, v56
	v_sub_f32_e32 v56, v203, v48
	v_exp_f32_e32 v56, v56
	v_cvt_pk_bf16_f32 v179, v212, v213
	ds_read2_b64 v[180:183], v51 offset0:128 offset1:132
	v_cvt_pk_bf16_f32 v198, v197, v198
	v_add_f32_e32 v58, v56, v57
	v_sub_f32_e32 v57, v204, v48
	v_exp_f32_e32 v57, v57
	s_waitcnt lgkmcnt(0)
	v_mfma_f32_16x16x32_bf16 v[180:183], v[180:183], v[176:179], 0
	v_add_f32_e32 v59, v57, v58
	v_exp_f32_e32 v58, v44
	v_cvt_pk_bf16_f32 v199, v199, v200
	v_cvt_pk_bf16_f32 v200, v216, v217
	v_cvt_pk_bf16_f32 v201, v218, v219
	v_add_f32_e32 v44, v58, v59
	v_exp_f32_e32 v59, v45
	v_sub_f32_e32 v45, v49, v48
	v_exp_f32_e32 v60, v45
	v_sub_f32_e32 v45, v50, v48
	v_exp_f32_e32 v61, v45
	v_add_f32_e32 v44, v59, v44
	v_add_f32_e32 v44, v60, v44
	v_add_u32_e32 v50, 0x8000, v160
	v_add_f32_e32 v44, v61, v44
	ds_bpermute_b32 v45, v53, v44
	ds_read2_b64 v[202:205], v50 offset0:160 offset1:164
	s_waitcnt lgkmcnt(0)
	v_mfma_f32_16x16x32_bf16 v[202:205], v[202:205], v[176:179], 0
	v_add_f32_e32 v45, v44, v45
	ds_bpermute_b32 v49, v54, v45
	v_fma_f32 v44, v55, s12, -v48
	v_add_u32_e32 v48, 0x6800, v161
	ds_read2_b64 v[212:215], v48 offset0:128 offset1:132
	v_cvt_pk_bf16_f32 v184, v185, v188
	s_waitcnt lgkmcnt(1)
	v_add_f32_e32 v45, v45, v49
	v_add_u32_e32 v49, 0x9800, v160
	ds_read2_b64 v[208:211], v49 offset0:192 offset1:196
	s_waitcnt lgkmcnt(0)
	v_mfma_f32_16x16x32_bf16 v[208:211], v[208:211], v[176:179], 0
	v_cvt_pk_bf16_f32 v185, v189, v190
	ds_read2_b64 v[188:191], v51 offset0:144 offset1:148
	v_cvt_pk_bf16_f32 v186, v174, v173
	v_mfma_f32_16x16x32_bf16 v[176:179], v[212:215], v[176:179], 0
	ds_read2_b64 v[212:215], v51 offset0:136 offset1:140
	v_cvt_pk_bf16_f32 v187, v194, v196
	v_cvt_pk_bf16_f32 v167, v167, v168
	s_waitcnt lgkmcnt(0)
	v_mfma_f32_16x16x32_bf16 v[180:183], v[212:215], v[198:201], v[180:183]
	ds_read2_b64 v[212:215], v50 offset0:168 offset1:172
	v_cvt_pk_bf16_f32 v168, v169, v170
	v_cvt_pk_bf16_f32 v169, v171, v172
	s_waitcnt lgkmcnt(0)
	v_mfma_f32_16x16x32_bf16 v[202:205], v[212:215], v[198:201], v[202:205]
	ds_read2_b64 v[212:215], v49 offset0:200 offset1:204
	ds_read2_b64 v[170:173], v51 offset0:152 offset1:156
	v_cvt_pk_bf16_f32 v166, v165, v166
	s_waitcnt lgkmcnt(1)
	v_mfma_f32_16x16x32_bf16 v[208:211], v[212:215], v[198:201], v[208:211]
	ds_read2_b64 v[212:215], v48 offset0:136 offset1:140
	ds_read2_b64 v[192:195], v49 offset0:208 offset1:212
	v_exp_f32_e32 v44, v44
	s_waitcnt lgkmcnt(1)
	v_mfma_f32_16x16x32_bf16 v[176:179], v[212:215], v[198:201], v[176:179]
	ds_read2_b64 v[196:199], v48 offset0:144 offset1:148
	v_add_f32_e32 v44, v44, v45
	v_div_scale_f32 v45, s[6:7], v44, v44, 1.0
	v_mfma_f32_16x16x32_bf16 v[180:183], v[188:191], v[184:187], v[180:183]
	ds_read2_b64 v[188:191], v50 offset0:176 offset1:180
	s_waitcnt lgkmcnt(1)
	v_mfma_f32_16x16x32_bf16 v[174:177], v[196:199], v[184:187], v[176:179]
	v_mfma_f32_16x16x32_bf16 v[170:173], v[170:173], v[166:169], v[180:183]
	s_nop 3
	ds_read2_b64 v[178:181], v50 offset0:184 offset1:188
	s_waitcnt lgkmcnt(1)
	v_mfma_f32_16x16x32_bf16 v[188:191], v[188:191], v[184:187], v[202:205]
	v_mfma_f32_16x16x32_bf16 v[192:195], v[192:195], v[184:187], v[208:211]
	ds_read2_b64 v[182:185], v49 offset0:216 offset1:220
	s_waitcnt lgkmcnt(1)
	v_mfma_f32_16x16x32_bf16 v[178:181], v[178:181], v[166:169], v[188:191]
	s_nop 3
	ds_read2_b64 v[186:189], v48 offset0:152 offset1:156
	s_waitcnt lgkmcnt(1)
	v_mfma_f32_16x16x32_bf16 v[182:185], v[182:185], v[166:169], v[192:195]
	s_waitcnt lgkmcnt(0)
	v_mfma_f32_16x16x32_bf16 v[166:169], v[186:189], v[166:169], v[174:177]
	s_nop 2
	v_cvt_pk_bf16_f32 v175, v80, v81
	v_cvt_pk_bf16_f32 v176, v82, v83
	ds_read2_b64 v[80:83], v51 offset0:160 offset1:164
	v_cvt_pk_bf16_f32 v174, v62, v63
	v_cvt_pk_bf16_f32 v177, v163, v164
	s_waitcnt lgkmcnt(0)
	s_nop 0
	v_mfma_f32_16x16x32_bf16 v[80:83], v[80:83], v[174:177], v[170:173]
	s_nop 2
	ds_read2_b64 v[170:173], v50 offset0:192 offset1:196
	s_waitcnt lgkmcnt(0)
	v_mfma_f32_16x16x32_bf16 v[170:173], v[170:173], v[174:177], v[178:181]
	s_nop 2
	ds_read2_b64 v[178:181], v49 offset0:224 offset1:228
	s_waitcnt lgkmcnt(0)
	v_mfma_f32_16x16x32_bf16 v[178:181], v[178:181], v[174:177], v[182:185]
	s_nop 2
	ds_read2_b64 v[182:185], v48 offset0:160 offset1:164
	s_waitcnt lgkmcnt(0)
	v_mfma_f32_16x16x32_bf16 v[164:167], v[182:185], v[174:177], v[166:169]
	v_cvt_pk_bf16_f32 v177, v60, v61
	ds_read2_b64 v[60:63], v50 offset0:200 offset1:204
	v_cvt_pk_bf16_f32 v175, v56, v57
	v_cvt_pk_bf16_f32 v176, v58, v59
	ds_read2_b64 v[56:59], v51 offset0:168 offset1:172
	v_cvt_pk_bf16_f32 v174, v46, v47
	v_rcp_f32_e32 v46, v45
	s_waitcnt lgkmcnt(1)
	v_mfma_f32_16x16x32_bf16 v[60:63], v[60:63], v[174:177], v[170:173]
	v_fma_f32 v47, -v45, v46, 1.0
	s_nop 1
	ds_read2_b64 v[168:171], v48 offset0:168 offset1:172
	v_fmac_f32_e32 v46, v47, v46
	s_waitcnt lgkmcnt(1)
	v_mfma_f32_16x16x32_bf16 v[56:59], v[56:59], v[174:177], v[80:83]
	v_div_scale_f32 v47, vcc, 1.0, v44, 1.0
	v_mul_f32_e32 v163, v47, v46
	s_nop 0
	ds_read2_b64 v[80:83], v49 offset0:232 offset1:236
	s_waitcnt lgkmcnt(1)
	v_mfma_f32_16x16x32_bf16 v[164:167], v[168:171], v[174:177], v[164:167]
	v_fma_f32 v168, -v45, v163, v47
	v_fmac_f32_e32 v163, v168, v46
	v_fma_f32 v45, -v45, v163, v47
	v_div_fmas_f32 v45, v45, v46, v163
	v_div_fixup_f32 v44, v45, v44, 1.0
	v_or_b32_e32 v46, s2, v84
	v_mov_b32_e32 v47, v0
	s_waitcnt lgkmcnt(0)
	v_mfma_f32_16x16x32_bf16 v[80:83], v[80:83], v[174:177], v[178:181]
	v_lshlrev_b64 v[46:47], 11, v[46:47]
	v_pk_mul_f32 v[56:57], v[44:45], v[56:57] op_sel_hi:[0,1]
	v_pk_mul_f32 v[58:59], v[44:45], v[58:59] op_sel_hi:[0,1]
	v_lshl_add_u64 v[46:47], v[2:3], 0, v[46:47]
	v_cvt_pk_bf16_f32 v56, v56, v57
	v_cvt_pk_bf16_f32 v57, v58, v59
	ds_write_b64 v220, v[56:57]
	v_pk_mul_f32 v[56:57], v[44:45], v[60:61] op_sel_hi:[0,1]
	v_pk_mul_f32 v[58:59], v[44:45], v[62:63] op_sel_hi:[0,1]
	v_cvt_pk_bf16_f32 v56, v56, v57
	v_cvt_pk_bf16_f32 v57, v58, v59
	ds_write_b64 v220, v[56:57] offset:32
	v_pk_mul_f32 v[56:57], v[44:45], v[80:81] op_sel_hi:[0,1]
	v_pk_mul_f32 v[58:59], v[44:45], v[82:83] op_sel_hi:[0,1]
	v_cvt_pk_bf16_f32 v56, v56, v57
	v_cvt_pk_bf16_f32 v57, v58, v59
	ds_write_b64 v220, v[56:57] offset:64
	v_pk_mul_f32 v[56:57], v[44:45], v[164:165] op_sel_hi:[0,1]
	v_pk_mul_f32 v[44:45], v[44:45], v[166:167] op_sel_hi:[0,1]
	v_cvt_pk_bf16_f32 v56, v56, v57
	v_cvt_pk_bf16_f32 v57, v44, v45
	ds_write_b64 v220, v[56:57] offset:96
	s_waitcnt lgkmcnt(0)
	ds_read_b128 v[226:229], v221
	ds_read_b128 v[230:233], v221 offset:1152
	s_mov_b32 s98, 0x0
	s_mov_b32 s99, 0
	v_lshl_add_u64 v[224:225], v[222:223], 0, s[98:99]
	s_waitcnt lgkmcnt(1)
	global_store_dwordx4 v[224:225], v[226:229], off sc1
	s_mov_b32 s98, 0x4000
	v_lshl_add_u64 v[224:225], v[222:223], 0, s[98:99]
	s_waitcnt lgkmcnt(0)
	global_store_dwordx4 v[224:225], v[230:233], off sc1
	ds_read_b128 v[44:47], v156
	ds_read_b128 v[56:59], v156 offset:64
	s_waitcnt lgkmcnt(1)
	v_mfma_f32_16x16x32_bf16 v[44:47], v[44:47], v[40:43], 0
	v_cndmask_b32_e64 v163, v240, v108, s[68:69]
	ds_read_b128 v[60:63], v156 offset:2368
	ds_read_b128 v[172:175], v156 offset:11584
	s_waitcnt lgkmcnt(2)
	v_mfma_f32_16x16x32_bf16 v[44:47], v[56:59], v[36:39], v[44:47]
	ds_read_b128 v[176:179], v156 offset:13888
	ds_read_b128 v[180:183], v158 offset:64
	ds_read_b128 v[184:187], v156 offset:18496
	ds_read_b128 v[190:193], v156 offset:20800
	ds_read_b128 v[196:199], v156 offset:23104
	s_nop 2
	v_fma_f32 v59, v52, v163, v44
	v_add_f32_e32 v44, -1.0, v163
	v_fma_f32 v58, v52, |v44|, v45
	v_add_f32_e32 v45, -2.0, v163
	v_fma_f32 v57, v52, |v45|, v46
	v_add_f32_e32 v45, 0xc0400000, v163
	v_max3_f32 v44, v1, v59, v58
	v_fma_f32 v56, v52, |v45|, v47
	v_max3_f32 v80, v44, v57, v56
	ds_read_b128 v[44:47], v156 offset:2304
	s_waitcnt lgkmcnt(0)
	v_mfma_f32_16x16x32_bf16 v[44:47], v[44:47], v[40:43], 0
	v_mfma_f32_16x16x32_bf16 v[44:47], v[60:63], v[36:39], v[44:47]
	v_add_f32_e32 v60, 0xc1800000, v163
	s_nop 6
	v_fma_f32 v63, v52, |v60|, v44
	v_add_f32_e32 v44, 0xc1880000, v163
	v_fma_f32 v62, v52, |v44|, v45
	v_add_f32_e32 v45, 0xc1900000, v163
	v_fma_f32 v61, v52, |v45|, v46
	v_add_f32_e32 v45, 0xc1980000, v163
	v_max3_f32 v44, v80, v63, v62
	v_fma_f32 v60, v52, |v45|, v47
	v_max3_f32 v164, v44, v61, v60
	ds_read_b128 v[44:47], v156 offset:4608
	ds_read_b128 v[80:83], v156 offset:4672
	s_waitcnt lgkmcnt(1)
	v_mfma_f32_16x16x32_bf16 v[44:47], v[44:47], v[40:43], 0
	s_waitcnt lgkmcnt(0)
	v_mfma_f32_16x16x32_bf16 v[44:47], v[80:83], v[36:39], v[44:47]
	v_add_f32_e32 v80, 0xc2000000, v163
	s_nop 6
	v_fma_f32 v83, v52, |v80|, v44
	v_add_f32_e32 v44, 0xc2040000, v163
	v_fma_f32 v82, v52, |v44|, v45
	v_add_f32_e32 v45, 0xc2080000, v163
	v_fma_f32 v81, v52, |v45|, v46
	v_add_f32_e32 v45, 0xc20c0000, v163
	v_max3_f32 v44, v164, v83, v82
	v_fma_f32 v80, v52, |v45|, v47
	v_max3_f32 v168, v44, v81, v80
	ds_read_b128 v[44:47], v157
	ds_read_b128 v[164:167], v157 offset:64
	s_waitcnt lgkmcnt(1)
	v_mfma_f32_16x16x32_bf16 v[44:47], v[44:47], v[40:43], 0
	s_waitcnt lgkmcnt(0)
	v_mfma_f32_16x16x32_bf16 v[44:47], v[164:167], v[36:39], v[44:47]
	v_add_f32_e32 v164, 0xc2400000, v163
	s_nop 6
	v_fma_f32 v166, v52, |v164|, v44
	v_add_f32_e32 v44, 0xc2440000, v163
	v_fma_f32 v165, v52, |v44|, v45
	v_add_f32_e32 v45, 0xc2480000, v163
	v_fma_f32 v164, v52, |v45|, v46
	v_add_f32_e32 v45, 0xc24c0000, v163
	v_max3_f32 v44, v168, v166, v165
	v_fma_f32 v163, v52, |v45|, v47
	v_max3_f32 v167, v44, v164, v163
	ds_read_b128 v[44:47], v156 offset:9216
	ds_read_b128 v[168:171], v156 offset:9280
	s_waitcnt lgkmcnt(1)
	v_mfma_f32_16x16x32_bf16 v[44:47], v[44:47], v[40:43], 0
	s_waitcnt lgkmcnt(0)
	v_mfma_f32_16x16x32_bf16 v[44:47], v[168:171], v[36:39], v[44:47]
	v_cndmask_b32_e64 v171, v108, v240, s[66:67]
	v_add_f32_e32 v168, 0xc2800000, v171
	s_nop 5
	v_fma_f32 v170, v52, |v168|, v44
	v_add_f32_e32 v44, 0xc2820000, v171
	v_fma_f32 v169, v52, |v44|, v45
	v_add_f32_e32 v45, 0xc2840000, v171
	v_fma_f32 v168, v52, |v45|, v46
	v_add_f32_e32 v45, 0xc2860000, v171
	v_max3_f32 v44, v167, v170, v169
	v_fma_f32 v167, v52, |v45|, v47
	v_max3_f32 v171, v44, v168, v167
	ds_read_b128 v[44:47], v156 offset:11520
	s_waitcnt lgkmcnt(0)
	v_mfma_f32_16x16x32_bf16 v[44:47], v[44:47], v[40:43], 0
	v_mfma_f32_16x16x32_bf16 v[44:47], v[172:175], v[36:39], v[44:47]
	v_cndmask_b32_e64 v175, v108, v240, s[70:71]
	v_add_f32_e32 v172, 0xc2a00000, v175
	s_nop 5
	v_fma_f32 v174, v52, |v172|, v44
	v_add_f32_e32 v44, 0xc2a20000, v175
	v_fma_f32 v173, v52, |v44|, v45
	v_add_f32_e32 v45, 0xc2a40000, v175
	v_fma_f32 v172, v52, |v45|, v46
	v_add_f32_e32 v45, 0xc2a60000, v175
	v_max3_f32 v44, v171, v174, v173
	v_fma_f32 v171, v52, |v45|, v47
	v_max3_f32 v175, v44, v172, v171
	ds_read_b128 v[44:47], v156 offset:13824
	s_waitcnt lgkmcnt(0)
	v_mfma_f32_16x16x32_bf16 v[44:47], v[44:47], v[40:43], 0
	v_mfma_f32_16x16x32_bf16 v[44:47], v[176:179], v[36:39], v[44:47]
	v_cndmask_b32_e64 v179, v108, v240, s[72:73]
	v_add_f32_e32 v176, 0xc2c00000, v179
	s_nop 5
	v_fma_f32 v178, v52, |v176|, v44
	v_add_f32_e32 v44, 0xc2c20000, v179
	v_fma_f32 v177, v52, |v44|, v45
	v_add_f32_e32 v45, 0xc2c40000, v179
	v_fma_f32 v176, v52, |v45|, v46
	v_add_f32_e32 v45, 0xc2c60000, v179
	v_max3_f32 v44, v175, v178, v177
	v_fma_f32 v175, v52, |v45|, v47
	v_max3_f32 v179, v44, v176, v175
	ds_read_b128 v[44:47], v158
	s_waitcnt lgkmcnt(0)
	v_mfma_f32_16x16x32_bf16 v[44:47], v[44:47], v[40:43], 0
	v_mfma_f32_16x16x32_bf16 v[44:47], v[180:183], v[36:39], v[44:47]
	v_cndmask_b32_e64 v183, v108, v240, s[74:75]
	v_add_f32_e32 v180, 0xc2e00000, v183
	s_nop 5
	v_fma_f32 v182, v52, |v180|, v44
	v_add_f32_e32 v44, 0xc2e20000, v183
	v_fma_f32 v181, v52, |v44|, v45
	v_add_f32_e32 v45, 0xc2e40000, v183
	v_fma_f32 v180, v52, |v45|, v46
	v_add_f32_e32 v45, 0xc2e60000, v183
	v_max3_f32 v44, v179, v182, v181
	v_fma_f32 v179, v52, |v45|, v47
	v_max3_f32 v183, v44, v180, v179
	ds_read_b128 v[44:47], v156 offset:18432
	s_waitcnt lgkmcnt(0)
	v_mfma_f32_16x16x32_bf16 v[44:47], v[44:47], v[40:43], 0
	v_mfma_f32_16x16x32_bf16 v[44:47], v[184:187], v[36:39], v[44:47]
	ds_read_b128 v[186:189], v156 offset:20736
	v_cndmask_b32_e64 v184, v240, v108, s[76:77]
	s_waitcnt lgkmcnt(0)
	v_mfma_f32_16x16x32_bf16 v[186:189], v[186:189], v[40:43], 0
	s_nop 3
	v_fma_f32 v185, v52, v109, v44
	v_fma_f32 v45, v52, v110, v45
	v_max3_f32 v183, v183, v185, v45
	v_mfma_f32_16x16x32_bf16 v[192:195], v[190:193], v[36:39], v[186:189]
	v_fma_f32 v44, v52, v111, v46
	v_fmac_f32_e32 v47, v52, v112
	v_max3_f32 v46, v183, v44, v47
	v_add_f32_e32 v186, 0xc3200000, v184
	s_nop 3
	v_fma_f32 v191, v52, |v113|, v192
	v_fma_f32 v190, v52, |v114|, v193
	v_max3_f32 v183, v46, v191, v190
	v_fma_f32 v189, v52, |v115|, v194
	v_fma_f32 v46, v52, |v116|, v195
	ds_read_b128 v[192:195], v156 offset:23040
	s_waitcnt lgkmcnt(0)
	v_mfma_f32_16x16x32_bf16 v[192:195], v[192:195], v[40:43], 0
	v_max3_f32 v183, v183, v189, v46
	v_mfma_f32_16x16x32_bf16 v[192:195], v[196:199], v[36:39], v[192:195]
	s_nop 7
	v_fma_f32 v196, v52, |v186|, v192
	v_add_f32_e32 v186, 0xc3210000, v184
	v_fma_f32 v197, v52, |v186|, v193
	v_add_f32_e32 v186, 0xc3220000, v184
	v_fma_f32 v198, v52, |v186|, v194
	v_add_f32_e32 v186, 0xc3230000, v184
	v_fma_f32 v199, v52, |v186|, v195
	ds_read_b128 v[192:195], v159
	s_waitcnt lgkmcnt(0)
	v_mfma_f32_16x16x32_bf16 v[40:43], v[192:195], v[40:43], 0
	ds_read_b128 v[192:195], v159 offset:64
	v_max3_f32 v183, v183, v196, v197
	v_max3_f32 v183, v183, v198, v199
	s_waitcnt lgkmcnt(0)
	v_mfma_f32_16x16x32_bf16 v[36:39], v[192:195], v[36:39], v[40:43]
	s_nop 2
	v_add_f32_e32 v40, 0xc3300000, v184
	v_add_f32_e32 v41, 0xc3320000, v184
	s_nop 2
	v_fma_f32 v36, v52, |v40|, v36
	v_add_f32_e32 v40, 0xc3310000, v184
	v_fma_f32 v37, v52, |v40|, v37
	v_fma_f32 v38, v52, |v41|, v38
	v_add_f32_e32 v41, 0xc3330000, v184
	v_max3_f32 v40, v183, v36, v37
	v_fma_f32 v39, v52, |v41|, v39
	v_max3_f32 v40, v40, v38, v39
	ds_bpermute_b32 v41, v53, v40
	s_waitcnt lgkmcnt(0)
	v_max_f32_e32 v41, v41, v41
	v_max_f32_e32 v40, v40, v41
	ds_bpermute_b32 v41, v54, v40
	s_waitcnt lgkmcnt(0)
	v_max_f32_e32 v41, v41, v41
	v_max_f32_e32 v40, v40, v41
	v_sub_f32_e32 v41, v59, v40
	v_exp_f32_e32 v200, v41
	v_sub_f32_e32 v42, v58, v40
	v_exp_f32_e32 v201, v42
	v_sub_f32_e32 v42, v57, v40
	v_exp_f32_e32 v202, v42
	v_sub_f32_e32 v42, v56, v40
	v_exp_f32_e32 v203, v42
	v_sub_f32_e32 v42, v63, v40
	v_add_f32_e32 v41, 0, v200
	v_exp_f32_e32 v204, v42
	v_sub_f32_e32 v42, v62, v40
	v_add_f32_e32 v41, v201, v41
	v_exp_f32_e32 v205, v42
	v_sub_f32_e32 v42, v61, v40
	v_add_f32_e32 v41, v202, v41
	v_exp_f32_e32 v208, v42
	v_sub_f32_e32 v42, v60, v40
	v_add_f32_e32 v41, v203, v41
	v_exp_f32_e32 v209, v42
	v_sub_f32_e32 v42, v83, v40
	v_add_f32_e32 v41, v204, v41
	v_exp_f32_e32 v186, v42
	v_sub_f32_e32 v42, v82, v40
	v_add_f32_e32 v41, v205, v41
	v_exp_f32_e32 v187, v42
	v_sub_f32_e32 v42, v81, v40
	v_add_f32_e32 v41, v208, v41
	v_exp_f32_e32 v188, v42
	v_sub_f32_e32 v42, v80, v40
	v_add_f32_e32 v41, v209, v41
	v_exp_f32_e32 v192, v42
	v_sub_f32_e32 v42, v166, v40
	v_add_f32_e32 v41, v186, v41
	v_exp_f32_e32 v193, v42
	v_sub_f32_e32 v42, v165, v40
	v_add_f32_e32 v41, v187, v41
	v_exp_f32_e32 v194, v42
	v_sub_f32_e32 v42, v164, v40
	v_add_f32_e32 v41, v188, v41
	v_exp_f32_e32 v195, v42
	v_sub_f32_e32 v42, v163, v40
	v_add_f32_e32 v41, v192, v41
	v_exp_f32_e32 v212, v42
	v_sub_f32_e32 v42, v170, v40
	v_add_f32_e32 v41, v193, v41
	v_exp_f32_e32 v170, v42
	v_sub_f32_e32 v42, v169, v40
	v_add_f32_e32 v41, v194, v41
	v_exp_f32_e32 v169, v42
	v_sub_f32_e32 v42, v168, v40
	v_add_f32_e32 v41, v195, v41
	v_exp_f32_e32 v183, v42
	v_sub_f32_e32 v42, v167, v40
	v_add_f32_e32 v41, v212, v41
	v_exp_f32_e32 v184, v42
	v_sub_f32_e32 v42, v174, v40
	v_add_f32_e32 v41, v170, v41
	v_exp_f32_e32 v174, v42
	v_sub_f32_e32 v42, v173, v40
	v_add_f32_e32 v41, v169, v41
	v_exp_f32_e32 v173, v42
	v_sub_f32_e32 v42, v172, v40
	v_add_f32_e32 v41, v183, v41
	v_exp_f32_e32 v172, v42
	v_sub_f32_e32 v42, v171, v40
	v_add_f32_e32 v41, v184, v41
	v_exp_f32_e32 v171, v42
	v_sub_f32_e32 v42, v178, v40
	v_add_f32_e32 v41, v174, v41
	v_exp_f32_e32 v82, v42
	v_sub_f32_e32 v42, v177, v40
	v_add_f32_e32 v41, v173, v41
	v_exp_f32_e32 v83, v42
	v_sub_f32_e32 v42, v176, v40
	v_add_f32_e32 v41, v172, v41
	v_exp_f32_e32 v163, v42
	v_sub_f32_e32 v42, v175, v40
	v_add_f32_e32 v41, v171, v41
	v_exp_f32_e32 v164, v42
	v_sub_f32_e32 v42, v182, v40
	v_add_f32_e32 v41, v82, v41
	v_exp_f32_e32 v165, v42
	v_sub_f32_e32 v42, v181, v40
	v_add_f32_e32 v41, v83, v41
	v_exp_f32_e32 v166, v42
	v_sub_f32_e32 v42, v180, v40
	v_add_f32_e32 v41, v163, v41
	v_exp_f32_e32 v167, v42
	v_sub_f32_e32 v42, v179, v40
	v_add_f32_e32 v41, v164, v41
	v_exp_f32_e32 v168, v42
	v_sub_f32_e32 v42, v185, v40
	v_add_f32_e32 v41, v165, v41
	v_exp_f32_e32 v58, v42
	v_sub_f32_e32 v42, v45, v40
	v_add_f32_e32 v41, v166, v41
	v_exp_f32_e32 v59, v42
	v_sub_f32_e32 v42, v44, v40
	v_add_f32_e32 v41, v167, v41
	v_exp_f32_e32 v60, v42
	v_sub_f32_e32 v42, v47, v40
	v_add_f32_e32 v41, v168, v41
	v_exp_f32_e32 v61, v42
	v_sub_f32_e32 v42, v191, v40
	v_add_f32_e32 v41, v58, v41
	v_exp_f32_e32 v62, v42
	v_sub_f32_e32 v42, v190, v40
	v_add_f32_e32 v41, v59, v41
	v_exp_f32_e32 v63, v42
	v_sub_f32_e32 v42, v189, v40
	v_add_f32_e32 v41, v60, v41
	v_exp_f32_e32 v80, v42
	v_sub_f32_e32 v42, v46, v40
	v_add_f32_e32 v41, v61, v41
	v_exp_f32_e32 v81, v42
	v_sub_f32_e32 v42, v196, v40
	v_add_f32_e32 v41, v62, v41
	v_exp_f32_e32 v42, v42
	v_sub_f32_e32 v43, v197, v40
	v_add_f32_e32 v41, v63, v41
	v_exp_f32_e32 v43, v43
	v_sub_f32_e32 v44, v198, v40
	v_add_f32_e32 v41, v80, v41
	v_exp_f32_e32 v44, v44
	v_sub_f32_e32 v45, v199, v40
	v_add_f32_e32 v41, v81, v41
	v_exp_f32_e32 v45, v45
	v_sub_f32_e32 v36, v36, v40
	v_add_f32_e32 v41, v42, v41
	v_exp_f32_e32 v46, v36
	v_sub_f32_e32 v37, v37, v40
	v_add_f32_e32 v41, v43, v41
	v_exp_f32_e32 v47, v37
	v_sub_f32_e32 v37, v38, v40
	v_add_f32_e32 v41, v44, v41
	v_exp_f32_e32 v56, v37
	v_sub_f32_e32 v37, v39, v40
	v_add_f32_e32 v41, v45, v41
	v_exp_f32_e32 v57, v37
	v_add_f32_e32 v36, v46, v41
	v_add_f32_e32 v36, v47, v36
	v_add_f32_e32 v36, v56, v36
	v_add_f32_e32 v36, v57, v36
	ds_bpermute_b32 v37, v53, v36
	ds_read2_b64 v[176:179], v51 offset0:128 offset1:132
	v_cvt_pk_bf16_f32 v186, v186, v187
	v_cvt_pk_bf16_f32 v187, v188, v192
	v_cvt_pk_bf16_f32 v188, v193, v194
	s_waitcnt lgkmcnt(1)
	v_add_f32_e32 v36, v36, v37
	ds_bpermute_b32 v37, v54, v36
	ds_read2_b64 v[190:193], v51 offset0:136 offset1:140
	v_fma_f32 v38, v55, s12, -v40
	v_exp_f32_e32 v40, v38
	v_cvt_pk_bf16_f32 v38, v204, v205
	s_waitcnt lgkmcnt(1)
	v_add_f32_e32 v41, v36, v37
	v_cvt_pk_bf16_f32 v36, v200, v201
	v_cvt_pk_bf16_f32 v37, v202, v203
	v_cvt_pk_bf16_f32 v39, v208, v209
	ds_read2_b64 v[196:199], v50 offset0:160 offset1:164
	v_cvt_pk_bf16_f32 v189, v195, v212
	v_mfma_f32_16x16x32_bf16 v[176:179], v[176:179], v[36:39], 0
	ds_read2_b64 v[200:203], v49 offset0:192 offset1:196
	v_cvt_pk_bf16_f32 v180, v170, v169
	v_cvt_pk_bf16_f32 v181, v183, v184
	s_waitcnt lgkmcnt(2)
	v_mfma_f32_16x16x32_bf16 v[176:179], v[190:193], v[186:189], v[176:179]
	ds_read2_b64 v[190:193], v50 offset0:168 offset1:172
	v_cvt_pk_bf16_f32 v182, v174, v173
	v_cvt_pk_bf16_f32 v183, v172, v171
	s_waitcnt lgkmcnt(2)
	v_mfma_f32_16x16x32_bf16 v[196:199], v[196:199], v[36:39], 0
	ds_read2_b64 v[170:173], v51 offset0:144 offset1:148
	ds_read2_b64 v[208:211], v48 offset0:128 offset1:132
	v_cvt_pk_bf16_f32 v58, v58, v59
	s_waitcnt lgkmcnt(2)
	v_mfma_f32_16x16x32_bf16 v[190:193], v[190:193], v[186:189], v[196:199]
	v_cvt_pk_bf16_f32 v59, v60, v61
	s_nop 1
	ds_read2_b64 v[194:197], v49 offset0:200 offset1:204
	v_cvt_pk_bf16_f32 v61, v80, v81
	v_mfma_f32_16x16x32_bf16 v[200:203], v[200:203], v[36:39], 0
	v_cvt_pk_bf16_f32 v60, v62, v63
	v_cvt_pk_bf16_f32 v42, v42, v43
	v_cvt_pk_bf16_f32 v43, v44, v45
	s_waitcnt lgkmcnt(0)
	v_mfma_f32_16x16x32_bf16 v[194:197], v[194:197], v[186:189], v[200:203]
	v_cvt_pk_bf16_f32 v45, v56, v57
	s_nop 1
	ds_read2_b64 v[198:201], v48 offset0:136 offset1:140
	v_cvt_pk_bf16_f32 v44, v46, v47
	v_mfma_f32_16x16x32_bf16 v[170:173], v[170:173], v[180:183], v[176:179]
	v_add_f32_e32 v40, v40, v41
	v_div_scale_f32 v41, s[6:7], v40, v40, 1.0
	s_nop 0
	ds_read2_b64 v[174:177], v50 offset0:176 offset1:180
	v_mfma_f32_16x16x32_bf16 v[36:39], v[208:211], v[36:39], 0
	v_cvt_pk_bf16_f32 v179, v163, v164
	v_cvt_pk_bf16_f32 v178, v82, v83
	ds_read2_b64 v[80:83], v51 offset0:160 offset1:164
	s_waitcnt lgkmcnt(2)
	v_mfma_f32_16x16x32_bf16 v[36:39], v[198:201], v[186:189], v[36:39]
	ds_read2_b64 v[184:187], v49 offset0:208 offset1:212
	s_waitcnt lgkmcnt(2)
	v_mfma_f32_16x16x32_bf16 v[174:177], v[174:177], v[180:183], v[190:193]
	s_nop 2
	ds_read2_b64 v[188:191], v48 offset0:144 offset1:148
	s_waitcnt lgkmcnt(1)
	v_mfma_f32_16x16x32_bf16 v[184:187], v[184:187], v[180:183], v[194:197]
	s_waitcnt lgkmcnt(0)
	v_mfma_f32_16x16x32_bf16 v[36:39], v[188:191], v[180:183], v[36:39]
	v_cvt_pk_bf16_f32 v180, v165, v166
	v_cvt_pk_bf16_f32 v181, v167, v168
	ds_read2_b64 v[164:167], v51 offset0:152 offset1:156
	s_waitcnt lgkmcnt(0)
	v_mfma_f32_16x16x32_bf16 v[164:167], v[164:167], v[178:181], v[170:173]
	s_nop 2
	ds_read2_b64 v[168:171], v50 offset0:184 offset1:188
	v_mfma_f32_16x16x32_bf16 v[80:83], v[80:83], v[58:61], v[164:167]
	s_nop 2
	ds_read2_b64 v[164:167], v50 offset0:192 offset1:196
	s_waitcnt lgkmcnt(1)
	v_mfma_f32_16x16x32_bf16 v[168:171], v[168:171], v[178:181], v[174:177]
	s_nop 2
	ds_read2_b64 v[172:175], v49 offset0:216 offset1:220
	s_waitcnt lgkmcnt(1)
	v_mfma_f32_16x16x32_bf16 v[164:167], v[164:167], v[58:61], v[168:171]
	s_nop 2
	ds_read2_b64 v[168:171], v49 offset0:224 offset1:228
	s_waitcnt lgkmcnt(1)
	v_mfma_f32_16x16x32_bf16 v[172:175], v[172:175], v[178:181], v[184:187]
	s_nop 2
	ds_read2_b64 v[182:185], v48 offset0:152 offset1:156
	s_waitcnt lgkmcnt(1)
	v_mfma_f32_16x16x32_bf16 v[168:171], v[168:171], v[58:61], v[172:175]
	s_nop 2
	ds_read2_b64 v[172:175], v48 offset0:160 offset1:164
	s_waitcnt lgkmcnt(1)
	v_mfma_f32_16x16x32_bf16 v[36:39], v[182:185], v[178:181], v[36:39]
	s_waitcnt lgkmcnt(0)
	v_mfma_f32_16x16x32_bf16 v[36:39], v[172:175], v[58:61], v[36:39]
	ds_read2_b64 v[56:59], v51 offset0:168 offset1:172
	ds_read2_b64 v[60:63], v50 offset0:200 offset1:204
	s_waitcnt lgkmcnt(1)
	v_mfma_f32_16x16x32_bf16 v[56:59], v[56:59], v[42:45], v[80:83]
	s_nop 2
	ds_read2_b64 v[80:83], v49 offset0:232 offset1:236
	s_waitcnt lgkmcnt(1)
	v_mfma_f32_16x16x32_bf16 v[60:63], v[60:63], v[42:45], v[164:167]
	s_nop 2
	ds_read2_b64 v[164:167], v48 offset0:168 offset1:172
	s_waitcnt lgkmcnt(1)
	v_mfma_f32_16x16x32_bf16 v[80:83], v[80:83], v[42:45], v[168:171]
	s_waitcnt lgkmcnt(0)
	v_mfma_f32_16x16x32_bf16 v[36:39], v[164:167], v[42:45], v[36:39]
	v_rcp_f32_e32 v42, v41
	s_nop 0
	v_fma_f32 v43, -v41, v42, 1.0
	v_fmac_f32_e32 v42, v43, v42
	v_div_scale_f32 v43, vcc, 1.0, v40, 1.0
	v_mul_f32_e32 v44, v43, v42
	v_fma_f32 v45, -v41, v44, v43
	v_fmac_f32_e32 v44, v45, v42
	v_fma_f32 v41, -v41, v44, v43
	v_div_fmas_f32 v41, v41, v42, v44
	v_div_fixup_f32 v40, v41, v40, 1.0
	v_or_b32_e32 v42, s2, v97
	v_mov_b32_e32 v43, v0
	v_lshlrev_b64 v[42:43], 11, v[42:43]
	v_pk_mul_f32 v[44:45], v[40:41], v[56:57] op_sel_hi:[0,1]
	v_pk_mul_f32 v[46:47], v[40:41], v[58:59] op_sel_hi:[0,1]
	v_lshl_add_u64 v[42:43], v[2:3], 0, v[42:43]
	v_cvt_pk_bf16_f32 v44, v44, v45
	v_cvt_pk_bf16_f32 v45, v46, v47
	ds_write_b64 v220, v[44:45]
	v_pk_mul_f32 v[44:45], v[40:41], v[60:61] op_sel_hi:[0,1]
	v_pk_mul_f32 v[46:47], v[40:41], v[62:63] op_sel_hi:[0,1]
	v_cvt_pk_bf16_f32 v44, v44, v45
	v_cvt_pk_bf16_f32 v45, v46, v47
	ds_write_b64 v220, v[44:45] offset:32
	v_pk_mul_f32 v[44:45], v[40:41], v[80:81] op_sel_hi:[0,1]
	v_pk_mul_f32 v[46:47], v[40:41], v[82:83] op_sel_hi:[0,1]
	v_pk_mul_f32 v[36:37], v[40:41], v[36:37] op_sel_hi:[0,1]
	v_pk_mul_f32 v[38:39], v[40:41], v[38:39] op_sel_hi:[0,1]
	v_cvt_pk_bf16_f32 v44, v44, v45
	v_cvt_pk_bf16_f32 v45, v46, v47
	v_cvt_pk_bf16_f32 v36, v36, v37
	v_cvt_pk_bf16_f32 v37, v38, v39
	s_andn2_b64 vcc, exec, s[76:77]
	ds_write_b64 v220, v[44:45] offset:64
	ds_write_b64 v220, v[36:37] offset:96
	s_waitcnt lgkmcnt(0)
	ds_read_b128 v[226:229], v221
	ds_read_b128 v[230:233], v221 offset:1152
	s_mov_b32 s98, 0x8000
	s_mov_b32 s99, 0
	v_lshl_add_u64 v[224:225], v[222:223], 0, s[98:99]
	s_waitcnt lgkmcnt(1)
	global_store_dwordx4 v[224:225], v[226:229], off sc1
	s_mov_b32 s98, 0xc000
	v_lshl_add_u64 v[224:225], v[222:223], 0, s[98:99]
	s_waitcnt lgkmcnt(0)
	global_store_dwordx4 v[224:225], v[230:233], off sc1
	s_cbranch_vccnz .LBB0_755
	ds_read_b128 v[36:39], v156
	ds_read_b128 v[40:43], v156 offset:64
	v_cndmask_b32_e64 v63, v240, v117, s[68:69]
	s_and_b32 s2, s81, 0x7fffffc0
	s_waitcnt lgkmcnt(1)
	v_mfma_f32_16x16x32_bf16 v[36:39], v[36:39], v[32:35], 0
	ds_read_b128 v[180:183], v156 offset:20800
	ds_read_b128 v[186:189], v156 offset:23104
	s_waitcnt lgkmcnt(2)
	v_mfma_f32_16x16x32_bf16 v[36:39], v[40:43], v[28:31], v[36:39]
	ds_read_b128 v[40:43], v156 offset:2368
	s_nop 6
	v_fma_f32 v47, v52, v63, v36
	v_add_f32_e32 v36, -1.0, v63
	v_fma_f32 v46, v52, |v36|, v37
	v_add_f32_e32 v37, -2.0, v63
	v_fma_f32 v45, v52, |v37|, v38
	v_add_f32_e32 v37, 0xc0400000, v63
	v_max3_f32 v36, v1, v47, v46
	v_fma_f32 v44, v52, |v37|, v39
	v_max3_f32 v55, v36, v45, v44
	ds_read_b128 v[36:39], v156 offset:2304
	s_waitcnt lgkmcnt(0)
	v_mfma_f32_16x16x32_bf16 v[36:39], v[36:39], v[32:35], 0
	v_mfma_f32_16x16x32_bf16 v[36:39], v[40:43], v[28:31], v[36:39]
	v_add_f32_e32 v40, 0xc1800000, v63
	s_nop 6
	v_fma_f32 v58, v52, |v40|, v36
	v_add_f32_e32 v36, 0xc1880000, v63
	v_fma_f32 v57, v52, |v36|, v37
	v_add_f32_e32 v37, 0xc1900000, v63
	v_fma_f32 v56, v52, |v37|, v38
	v_add_f32_e32 v37, 0xc1980000, v63
	v_max3_f32 v36, v55, v58, v57
	v_fma_f32 v55, v52, |v37|, v39
	v_max3_f32 v59, v36, v56, v55
	ds_read_b128 v[36:39], v156 offset:4608
	ds_read_b128 v[40:43], v156 offset:4672
	s_waitcnt lgkmcnt(1)
	v_mfma_f32_16x16x32_bf16 v[36:39], v[36:39], v[32:35], 0
	s_waitcnt lgkmcnt(0)
	v_mfma_f32_16x16x32_bf16 v[36:39], v[40:43], v[28:31], v[36:39]
	v_add_f32_e32 v40, 0xc2000000, v63
	s_nop 6
	v_fma_f32 v62, v52, |v40|, v36
	v_add_f32_e32 v36, 0xc2040000, v63
	v_fma_f32 v61, v52, |v36|, v37
	v_add_f32_e32 v37, 0xc2080000, v63
	v_fma_f32 v60, v52, |v37|, v38
	v_add_f32_e32 v37, 0xc20c0000, v63
	v_max3_f32 v36, v59, v62, v61
	v_fma_f32 v59, v52, |v37|, v39
	v_max3_f32 v80, v36, v60, v59
	ds_read_b128 v[36:39], v157
	ds_read_b128 v[40:43], v157 offset:64
	s_waitcnt lgkmcnt(1)
	v_mfma_f32_16x16x32_bf16 v[36:39], v[36:39], v[32:35], 0
	s_waitcnt lgkmcnt(0)
	v_mfma_f32_16x16x32_bf16 v[36:39], v[40:43], v[28:31], v[36:39]
	v_add_f32_e32 v40, 0xc2400000, v63
	s_nop 6
	v_fma_f32 v82, v52, |v40|, v36
	v_add_f32_e32 v36, 0xc2440000, v63
	v_fma_f32 v81, v52, |v36|, v37
	v_add_f32_e32 v37, 0xc2480000, v63
	v_max3_f32 v36, v80, v82, v81
	v_fma_f32 v80, v52, |v37|, v38
	v_add_f32_e32 v37, 0xc24c0000, v63
	v_fma_f32 v63, v52, |v37|, v39
	v_max3_f32 v83, v36, v80, v63
	ds_read_b128 v[36:39], v156 offset:9216
	ds_read_b128 v[40:43], v156 offset:9280
	s_waitcnt lgkmcnt(1)
	v_mfma_f32_16x16x32_bf16 v[36:39], v[36:39], v[32:35], 0
	s_waitcnt lgkmcnt(0)
	v_mfma_f32_16x16x32_bf16 v[36:39], v[40:43], v[28:31], v[36:39]
	v_cndmask_b32_e64 v40, v117, v240, s[66:67]
	v_add_f32_e32 v41, 0xc2800000, v40
	s_nop 5
	v_fma_f32 v165, v52, |v41|, v36
	v_add_f32_e32 v36, 0xc2820000, v40
	v_fma_f32 v164, v52, |v36|, v37
	v_add_f32_e32 v37, 0xc2840000, v40
	v_fma_f32 v163, v52, |v37|, v38
	v_add_f32_e32 v37, 0xc2860000, v40
	v_max3_f32 v36, v83, v165, v164
	v_fma_f32 v83, v52, |v37|, v39
	v_max3_f32 v166, v36, v163, v83
	ds_read_b128 v[36:39], v156 offset:11520
	ds_read_b128 v[40:43], v156 offset:11584
	s_waitcnt lgkmcnt(1)
	v_mfma_f32_16x16x32_bf16 v[36:39], v[36:39], v[32:35], 0
	s_waitcnt lgkmcnt(0)
	v_mfma_f32_16x16x32_bf16 v[36:39], v[40:43], v[28:31], v[36:39]
	v_cndmask_b32_e64 v40, v117, v240, s[70:71]
	v_add_f32_e32 v41, 0xc2a00000, v40
	s_nop 5
	v_fma_f32 v169, v52, |v41|, v36
	v_add_f32_e32 v36, 0xc2a20000, v40
	v_fma_f32 v168, v52, |v36|, v37
	v_add_f32_e32 v37, 0xc2a40000, v40
	v_fma_f32 v167, v52, |v37|, v38
	v_add_f32_e32 v37, 0xc2a60000, v40
	v_max3_f32 v36, v166, v169, v168
	v_fma_f32 v166, v52, |v37|, v39
	v_max3_f32 v170, v36, v167, v166
	ds_read_b128 v[36:39], v156 offset:13824
	ds_read_b128 v[40:43], v156 offset:13888
	s_waitcnt lgkmcnt(1)
	v_mfma_f32_16x16x32_bf16 v[36:39], v[36:39], v[32:35], 0
	s_waitcnt lgkmcnt(0)
	v_mfma_f32_16x16x32_bf16 v[36:39], v[40:43], v[28:31], v[36:39]
	v_cndmask_b32_e64 v40, v117, v240, s[72:73]
	v_add_f32_e32 v41, 0xc2c00000, v40
	s_nop 5
	v_fma_f32 v173, v52, |v41|, v36
	v_add_f32_e32 v36, 0xc2c20000, v40
	v_fma_f32 v172, v52, |v36|, v37
	v_add_f32_e32 v37, 0xc2c40000, v40
	v_fma_f32 v171, v52, |v37|, v38
	v_add_f32_e32 v37, 0xc2c60000, v40
	v_max3_f32 v36, v170, v173, v172
	v_fma_f32 v170, v52, |v37|, v39
	v_max3_f32 v174, v36, v171, v170
	ds_read_b128 v[36:39], v158
	ds_read_b128 v[40:43], v158 offset:64
	s_waitcnt lgkmcnt(1)
	v_mfma_f32_16x16x32_bf16 v[36:39], v[36:39], v[32:35], 0
	s_waitcnt lgkmcnt(0)
	v_mfma_f32_16x16x32_bf16 v[36:39], v[40:43], v[28:31], v[36:39]
	v_cndmask_b32_e64 v40, v117, v240, s[74:75]
	v_add_f32_e32 v41, 0xc2e00000, v40
	s_nop 5
	v_fma_f32 v177, v52, |v41|, v36
	v_add_f32_e32 v36, 0xc2e20000, v40
	v_fma_f32 v176, v52, |v36|, v37
	v_add_f32_e32 v37, 0xc2e40000, v40
	v_fma_f32 v175, v52, |v37|, v38
	v_add_f32_e32 v37, 0xc2e60000, v40
	v_max3_f32 v36, v174, v177, v176
	v_fma_f32 v174, v52, |v37|, v39
	v_max3_f32 v178, v36, v175, v174
	ds_read_b128 v[36:39], v156 offset:18432
	ds_read_b128 v[40:43], v156 offset:18496
	s_waitcnt lgkmcnt(1)
	v_mfma_f32_16x16x32_bf16 v[36:39], v[36:39], v[32:35], 0
	s_waitcnt lgkmcnt(0)
	v_mfma_f32_16x16x32_bf16 v[36:39], v[40:43], v[28:31], v[36:39]
	s_nop 7
	v_fma_f32 v179, v52, v118, v36
	v_fma_f32 v37, v52, v119, v37
	v_max3_f32 v40, v178, v179, v37
	v_fma_f32 v36, v52, v120, v38
	v_fmac_f32_e32 v39, v52, v121
	v_max3_f32 v38, v40, v36, v39
	ds_read_b128 v[40:43], v156 offset:20736
	s_waitcnt lgkmcnt(0)
	v_mfma_f32_16x16x32_bf16 v[40:43], v[40:43], v[32:35], 0
	v_mfma_f32_16x16x32_bf16 v[40:43], v[180:183], v[28:31], v[40:43]
	ds_read_b128 v[180:183], v156 offset:23040
	s_waitcnt lgkmcnt(0)
	v_mfma_f32_16x16x32_bf16 v[180:183], v[180:183], v[32:35], 0
	s_nop 4
	v_fma_f32 v185, v52, v122, v40
	v_fma_f32 v40, v52, v123, v41
	v_max3_f32 v41, v38, v185, v40
	v_mfma_f32_16x16x32_bf16 v[180:183], v[186:189], v[28:31], v[180:183]
	v_fma_f32 v38, v52, v124, v42
	v_fmac_f32_e32 v43, v52, v125
	v_max3_f32 v41, v41, v38, v43
	s_nop 4
	v_fma_f32 v187, v52, |v126|, v180
	v_fma_f32 v188, v52, |v127|, v181
	v_fma_f32 v189, v52, |v128|, v182
	v_fma_f32 v190, v52, |v129|, v183
	ds_read_b128 v[180:183], v159
	s_waitcnt lgkmcnt(0)
	v_mfma_f32_16x16x32_bf16 v[32:35], v[180:183], v[32:35], 0
	ds_read_b128 v[180:183], v159 offset:64
	v_max3_f32 v41, v41, v187, v188
	v_max3_f32 v41, v41, v189, v190
	s_waitcnt lgkmcnt(0)
	v_mfma_f32_16x16x32_bf16 v[28:31], v[180:183], v[28:31], v[32:35]
	s_nop 7
	v_fma_f32 v28, v52, |v130|, v28
	v_fma_f32 v29, v52, |v131|, v29
	v_max3_f32 v32, v41, v28, v29
	v_fma_f32 v30, v52, |v132|, v30
	v_fma_f32 v31, v52, |v133|, v31
	v_max3_f32 v32, v32, v30, v31
	ds_bpermute_b32 v33, v53, v32
	s_waitcnt lgkmcnt(0)
	v_max_f32_e32 v33, v33, v33
	v_max_f32_e32 v32, v32, v33
	ds_bpermute_b32 v33, v54, v32
	s_waitcnt lgkmcnt(0)
	v_max_f32_e32 v33, v33, v33
	v_max_f32_e32 v32, v32, v33
	v_sub_f32_e32 v33, v47, v32
	v_exp_f32_e32 v191, v33
	v_sub_f32_e32 v34, v46, v32
	v_exp_f32_e32 v192, v34
	v_sub_f32_e32 v34, v45, v32
	v_exp_f32_e32 v193, v34
	v_sub_f32_e32 v34, v44, v32
	v_exp_f32_e32 v194, v34
	v_sub_f32_e32 v34, v58, v32
	v_add_f32_e32 v33, 0, v191
	v_exp_f32_e32 v195, v34
	v_sub_f32_e32 v34, v57, v32
	v_add_f32_e32 v33, v192, v33
	v_exp_f32_e32 v196, v34
	v_sub_f32_e32 v34, v56, v32
	v_add_f32_e32 v33, v193, v33
	v_exp_f32_e32 v197, v34
	v_sub_f32_e32 v34, v55, v32
	v_add_f32_e32 v33, v194, v33
	v_exp_f32_e32 v198, v34
	v_sub_f32_e32 v34, v62, v32
	v_add_f32_e32 v33, v195, v33
	v_exp_f32_e32 v178, v34
	v_sub_f32_e32 v34, v61, v32
	v_add_f32_e32 v33, v196, v33
	v_exp_f32_e32 v180, v34
	v_sub_f32_e32 v34, v60, v32
	v_add_f32_e32 v33, v197, v33
	v_exp_f32_e32 v181, v34
	v_sub_f32_e32 v34, v59, v32
	v_add_f32_e32 v33, v198, v33
	v_exp_f32_e32 v182, v34
	v_sub_f32_e32 v34, v82, v32
	v_add_f32_e32 v33, v178, v33
	v_exp_f32_e32 v183, v34
	v_sub_f32_e32 v34, v81, v32
	v_add_f32_e32 v33, v180, v33
	v_exp_f32_e32 v184, v34
	v_sub_f32_e32 v34, v80, v32
	v_add_f32_e32 v33, v181, v33
	v_exp_f32_e32 v186, v34
	v_sub_f32_e32 v34, v63, v32
	v_add_f32_e32 v33, v182, v33
	v_exp_f32_e32 v199, v34
	v_sub_f32_e32 v34, v165, v32
	v_add_f32_e32 v33, v183, v33
	v_exp_f32_e32 v81, v34
	v_sub_f32_e32 v34, v164, v32
	v_add_f32_e32 v33, v184, v33
	v_exp_f32_e32 v82, v34
	v_sub_f32_e32 v34, v163, v32
	v_add_f32_e32 v33, v186, v33
	v_exp_f32_e32 v163, v34
	v_sub_f32_e32 v34, v83, v32
	v_add_f32_e32 v33, v199, v33
	v_exp_f32_e32 v83, v34
	v_sub_f32_e32 v34, v169, v32
	v_add_f32_e32 v33, v81, v33
	v_exp_f32_e32 v164, v34
	v_sub_f32_e32 v34, v168, v32
	v_add_f32_e32 v33, v82, v33
	v_exp_f32_e32 v165, v34
	v_sub_f32_e32 v34, v167, v32
	v_add_f32_e32 v33, v163, v33
	v_exp_f32_e32 v167, v34
	v_sub_f32_e32 v34, v166, v32
	v_add_f32_e32 v33, v83, v33
	v_exp_f32_e32 v166, v34
	v_sub_f32_e32 v34, v173, v32
	v_add_f32_e32 v33, v164, v33
	v_exp_f32_e32 v57, v34
	v_sub_f32_e32 v34, v172, v32
	v_add_f32_e32 v33, v165, v33
	v_exp_f32_e32 v58, v34
	v_sub_f32_e32 v34, v171, v32
	v_add_f32_e32 v33, v167, v33
	v_exp_f32_e32 v59, v34
	v_sub_f32_e32 v34, v170, v32
	v_add_f32_e32 v33, v166, v33
	v_exp_f32_e32 v60, v34
	v_sub_f32_e32 v34, v177, v32
	v_add_f32_e32 v33, v57, v33
	v_exp_f32_e32 v61, v34
	v_sub_f32_e32 v34, v176, v32
	v_add_f32_e32 v33, v58, v33
	v_exp_f32_e32 v62, v34
	v_sub_f32_e32 v34, v175, v32
	v_add_f32_e32 v33, v59, v33
	v_exp_f32_e32 v63, v34
	v_sub_f32_e32 v34, v174, v32
	v_add_f32_e32 v33, v60, v33
	v_exp_f32_e32 v80, v34
	v_sub_f32_e32 v34, v179, v32
	v_add_f32_e32 v33, v61, v33
	v_exp_f32_e32 v42, v34
	v_sub_f32_e32 v34, v37, v32
	v_add_f32_e32 v33, v62, v33
	v_exp_f32_e32 v44, v34
	v_sub_f32_e32 v34, v36, v32
	v_add_f32_e32 v33, v63, v33
	v_exp_f32_e32 v45, v34
	v_sub_f32_e32 v34, v39, v32
	v_add_f32_e32 v33, v80, v33
	v_exp_f32_e32 v46, v34
	v_sub_f32_e32 v34, v185, v32
	v_add_f32_e32 v33, v42, v33
	v_exp_f32_e32 v47, v34
	v_sub_f32_e32 v34, v40, v32
	v_add_f32_e32 v33, v44, v33
	v_exp_f32_e32 v55, v34
	v_sub_f32_e32 v34, v38, v32
	v_add_f32_e32 v33, v45, v33
	v_exp_f32_e32 v56, v34
	v_sub_f32_e32 v34, v43, v32
	v_add_f32_e32 v33, v46, v33
	v_exp_f32_e32 v43, v34
	v_sub_f32_e32 v34, v187, v32
	v_add_f32_e32 v33, v47, v33
	v_exp_f32_e32 v34, v34
	v_sub_f32_e32 v35, v188, v32
	v_add_f32_e32 v33, v55, v33
	v_exp_f32_e32 v35, v35
	v_sub_f32_e32 v36, v189, v32
	v_add_f32_e32 v33, v56, v33
	v_exp_f32_e32 v36, v36
	v_sub_f32_e32 v37, v190, v32
	v_add_f32_e32 v33, v43, v33
	v_exp_f32_e32 v37, v37
	v_sub_f32_e32 v28, v28, v32
	v_add_f32_e32 v33, v34, v33
	v_exp_f32_e32 v38, v28
	v_sub_f32_e32 v29, v29, v32
	v_add_f32_e32 v33, v35, v33
	v_exp_f32_e32 v39, v29
	v_sub_f32_e32 v29, v30, v32
	v_add_f32_e32 v33, v36, v33
	v_exp_f32_e32 v40, v29
	v_sub_f32_e32 v29, v31, v32
	v_add_f32_e32 v33, v37, v33
	v_exp_f32_e32 v41, v29
	v_add_f32_e32 v28, v38, v33
	v_add_f32_e32 v28, v39, v28
	v_add_f32_e32 v28, v40, v28
	v_add_f32_e32 v28, v41, v28
	ds_bpermute_b32 v29, v53, v28
	ds_read2_b64 v[168:171], v51 offset0:128 offset1:132
	v_cvt_pk_bf16_f32 v176, v178, v180
	v_cvt_pk_bf16_f32 v177, v181, v182
	v_cvt_pk_bf16_f32 v178, v183, v184
	s_waitcnt lgkmcnt(1)
	v_add_f32_e32 v28, v28, v29
	ds_bpermute_b32 v29, v54, v28
	ds_read2_b64 v[180:183], v51 offset0:136 offset1:140
	v_sub_f32_e32 v30, v1, v32
	v_exp_f32_e32 v32, v30
	v_cvt_pk_bf16_f32 v30, v195, v196
	s_waitcnt lgkmcnt(1)
	v_add_f32_e32 v33, v28, v29
	v_cvt_pk_bf16_f32 v28, v191, v192
	v_cvt_pk_bf16_f32 v29, v193, v194
	v_cvt_pk_bf16_f32 v31, v197, v198
	ds_read2_b64 v[172:175], v50 offset0:160 offset1:164
	v_cvt_pk_bf16_f32 v179, v186, v199
	v_mfma_f32_16x16x32_bf16 v[168:171], v[168:171], v[28:31], 0
	ds_read2_b64 v[188:191], v49 offset0:192 offset1:196
	ds_read2_b64 v[192:195], v48 offset0:128 offset1:132
	ds_read2_b64 v[184:187], v48 offset0:136 offset1:140
	s_waitcnt lgkmcnt(4)
	v_mfma_f32_16x16x32_bf16 v[168:171], v[180:183], v[176:179], v[168:171]
	ds_read2_b64 v[180:183], v50 offset0:168 offset1:172
	v_cvt_pk_bf16_f32 v59, v59, v60
	v_cvt_pk_bf16_f32 v60, v61, v62
	s_waitcnt lgkmcnt(4)
	v_mfma_f32_16x16x32_bf16 v[172:175], v[172:175], v[28:31], 0
	v_cvt_pk_bf16_f32 v61, v63, v80
	v_cvt_pk_bf16_f32 v58, v57, v58
	v_cvt_pk_bf16_f32 v45, v45, v46
	s_waitcnt lgkmcnt(0)
	v_mfma_f32_16x16x32_bf16 v[172:175], v[180:183], v[176:179], v[172:175]
	ds_read2_b64 v[180:183], v49 offset0:200 offset1:204
	v_cvt_pk_bf16_f32 v46, v47, v55
	v_cvt_pk_bf16_f32 v47, v56, v43
	v_mfma_f32_16x16x32_bf16 v[188:191], v[188:191], v[28:31], 0
	v_cvt_pk_bf16_f32 v44, v42, v44
	v_cvt_pk_bf16_f32 v34, v34, v35
	v_cvt_pk_bf16_f32 v35, v36, v37
	v_mfma_f32_16x16x32_bf16 v[28:31], v[192:195], v[28:31], 0
	v_cvt_pk_bf16_f32 v36, v38, v39
	v_cvt_pk_bf16_f32 v37, v40, v41
	ds_read2_b64 v[38:41], v51 offset0:168 offset1:172
	s_waitcnt lgkmcnt(1)
	v_mfma_f32_16x16x32_bf16 v[180:183], v[180:183], v[176:179], v[188:191]
	v_add_f32_e32 v32, v32, v33
	v_div_scale_f32 v33, s[6:7], v32, v32, 1.0
	v_mfma_f32_16x16x32_bf16 v[28:31], v[184:187], v[176:179], v[28:31]
	v_cvt_pk_bf16_f32 v178, v164, v165
	v_cvt_pk_bf16_f32 v179, v167, v166
	ds_read2_b64 v[164:167], v51 offset0:144 offset1:148
	v_cvt_pk_bf16_f32 v176, v81, v82
	v_cvt_pk_bf16_f32 v177, v163, v83
	ds_read2_b64 v[80:83], v51 offset0:152 offset1:156
	s_waitcnt lgkmcnt(1)
	v_mfma_f32_16x16x32_bf16 v[164:167], v[164:167], v[176:179], v[168:171]
	s_nop 2
	ds_read2_b64 v[168:171], v50 offset0:176 offset1:180
	s_waitcnt lgkmcnt(1)
	v_mfma_f32_16x16x32_bf16 v[80:83], v[80:83], v[58:61], v[164:167]
	s_nop 2
	ds_read2_b64 v[164:167], v50 offset0:184 offset1:188
	s_waitcnt lgkmcnt(1)
	v_mfma_f32_16x16x32_bf16 v[168:171], v[168:171], v[176:179], v[172:175]
	s_nop 2
	ds_read2_b64 v[172:175], v49 offset0:208 offset1:212
	s_waitcnt lgkmcnt(1)
	v_mfma_f32_16x16x32_bf16 v[164:167], v[164:167], v[58:61], v[168:171]
	s_nop 2
	ds_read2_b64 v[168:171], v49 offset0:216 offset1:220
	s_waitcnt lgkmcnt(1)
	v_mfma_f32_16x16x32_bf16 v[172:175], v[172:175], v[176:179], v[180:183]
	s_nop 2
	ds_read2_b64 v[180:183], v48 offset0:144 offset1:148
	s_waitcnt lgkmcnt(1)
	v_mfma_f32_16x16x32_bf16 v[168:171], v[168:171], v[58:61], v[172:175]
	s_nop 2
	ds_read2_b64 v[172:175], v48 offset0:152 offset1:156
	s_waitcnt lgkmcnt(1)
	v_mfma_f32_16x16x32_bf16 v[28:31], v[180:183], v[176:179], v[28:31]
	s_waitcnt lgkmcnt(0)
	v_mfma_f32_16x16x32_bf16 v[28:31], v[172:175], v[58:61], v[28:31]
	ds_read2_b64 v[56:59], v51 offset0:160 offset1:164
	ds_read2_b64 v[60:63], v50 offset0:192 offset1:196
	s_waitcnt lgkmcnt(1)
	v_mfma_f32_16x16x32_bf16 v[56:59], v[56:59], v[44:47], v[80:83]
	s_nop 2
	ds_read2_b64 v[80:83], v49 offset0:224 offset1:228
	s_waitcnt lgkmcnt(1)
	v_mfma_f32_16x16x32_bf16 v[60:63], v[60:63], v[44:47], v[164:167]
	s_nop 2
	ds_read2_b64 v[164:167], v48 offset0:160 offset1:164
	s_waitcnt lgkmcnt(1)
	v_mfma_f32_16x16x32_bf16 v[80:83], v[80:83], v[44:47], v[168:171]
	s_waitcnt lgkmcnt(0)
	v_mfma_f32_16x16x32_bf16 v[28:31], v[164:167], v[44:47], v[28:31]
	ds_read2_b64 v[42:45], v50 offset0:200 offset1:204
	v_mfma_f32_16x16x32_bf16 v[38:41], v[38:41], v[34:37], v[56:59]
	s_waitcnt lgkmcnt(0)
	v_mfma_f32_16x16x32_bf16 v[42:45], v[42:45], v[34:37], v[60:63]
	s_nop 0
	ds_read2_b64 v[56:59], v49 offset0:232 offset1:236
	s_nop 0
	ds_read2_b64 v[60:63], v48 offset0:168 offset1:172
	s_waitcnt lgkmcnt(1)
	v_mfma_f32_16x16x32_bf16 v[56:59], v[56:59], v[34:37], v[80:83]
	s_waitcnt lgkmcnt(0)
	v_mfma_f32_16x16x32_bf16 v[28:31], v[60:63], v[34:37], v[28:31]
	v_rcp_f32_e32 v34, v33
	s_nop 0
	v_fma_f32 v35, -v33, v34, 1.0
	v_fmac_f32_e32 v34, v35, v34
	v_div_scale_f32 v35, vcc, 1.0, v32, 1.0
	v_mul_f32_e32 v36, v35, v34
	v_fma_f32 v37, -v33, v36, v35
	v_fmac_f32_e32 v36, v37, v34
	v_fma_f32 v33, -v33, v36, v35
	v_div_fmas_f32 v33, v33, v34, v36
	v_div_fixup_f32 v32, v33, v32, 1.0
	v_or_b32_e32 v34, s2, v98
	v_mov_b32_e32 v35, v0
	v_lshlrev_b64 v[34:35], 11, v[34:35]
	v_pk_mul_f32 v[36:37], v[32:33], v[38:39] op_sel_hi:[0,1]
	v_pk_mul_f32 v[38:39], v[32:33], v[40:41] op_sel_hi:[0,1]
	v_lshl_add_u64 v[34:35], v[2:3], 0, v[34:35]
	v_cvt_pk_bf16_f32 v36, v36, v37
	v_cvt_pk_bf16_f32 v37, v38, v39
	ds_write_b64 v220, v[36:37]
	v_pk_mul_f32 v[36:37], v[32:33], v[42:43] op_sel_hi:[0,1]
	v_pk_mul_f32 v[38:39], v[32:33], v[44:45] op_sel_hi:[0,1]
	v_cvt_pk_bf16_f32 v36, v36, v37
	v_cvt_pk_bf16_f32 v37, v38, v39
	ds_write_b64 v220, v[36:37] offset:32
	v_pk_mul_f32 v[36:37], v[32:33], v[56:57] op_sel_hi:[0,1]
	v_pk_mul_f32 v[38:39], v[32:33], v[58:59] op_sel_hi:[0,1]
	v_pk_mul_f32 v[28:29], v[32:33], v[28:29] op_sel_hi:[0,1]
	v_pk_mul_f32 v[30:31], v[32:33], v[30:31] op_sel_hi:[0,1]
	v_cvt_pk_bf16_f32 v36, v36, v37
	v_cvt_pk_bf16_f32 v37, v38, v39
	v_cvt_pk_bf16_f32 v28, v28, v29
	v_cvt_pk_bf16_f32 v29, v30, v31
	ds_write_b64 v220, v[36:37] offset:64
	ds_write_b64 v220, v[28:29] offset:96
	s_waitcnt lgkmcnt(0)
	ds_read_b128 v[226:229], v221
	ds_read_b128 v[230:233], v221 offset:1152
	s_mov_b32 s98, 0x10000
	s_mov_b32 s99, 0
	v_lshl_add_u64 v[224:225], v[222:223], 0, s[98:99]
	s_waitcnt lgkmcnt(1)
	global_store_dwordx4 v[224:225], v[226:229], off sc1
	s_mov_b32 s98, 0x14000
	v_lshl_add_u64 v[224:225], v[222:223], 0, s[98:99]
	s_waitcnt lgkmcnt(0)
	global_store_dwordx4 v[224:225], v[230:233], off sc1
	ds_read_b128 v[28:31], v156
	ds_read_b128 v[32:35], v156 offset:64
	s_waitcnt lgkmcnt(1)
	v_mfma_f32_16x16x32_bf16 v[28:31], v[28:31], v[24:27], 0
	v_cndmask_b32_e64 v36, v240, v134, s[68:69]
	ds_read_b128 v[176:179], v156 offset:23104
	s_waitcnt lgkmcnt(1)
	v_mfma_f32_16x16x32_bf16 v[28:31], v[32:35], v[20:23], v[28:31]
	ds_read_b128 v[32:35], v156 offset:2368
	s_nop 6
	v_fma_f32 v43, v52, v36, v28
	v_add_f32_e32 v28, -1.0, v36
	v_fma_f32 v42, v52, |v28|, v29
	v_add_f32_e32 v29, -2.0, v36
	v_fma_f32 v41, v52, |v29|, v30
	v_add_f32_e32 v29, 0xc0400000, v36
	v_max3_f32 v28, v1, v43, v42
	v_fma_f32 v40, v52, |v29|, v31
	v_max3_f32 v37, v28, v41, v40
	ds_read_b128 v[28:31], v156 offset:2304
	s_waitcnt lgkmcnt(0)
	v_mfma_f32_16x16x32_bf16 v[28:31], v[28:31], v[24:27], 0
	v_mfma_f32_16x16x32_bf16 v[28:31], v[32:35], v[20:23], v[28:31]
	v_add_f32_e32 v32, 0xc1800000, v36
	s_nop 6
	v_fma_f32 v47, v52, |v32|, v28
	v_add_f32_e32 v28, 0xc1880000, v36
	v_fma_f32 v46, v52, |v28|, v29
	v_add_f32_e32 v29, 0xc1900000, v36
	v_fma_f32 v45, v52, |v29|, v30
	v_add_f32_e32 v29, 0xc1980000, v36
	v_max3_f32 v28, v37, v47, v46
	v_fma_f32 v44, v52, |v29|, v31
	v_max3_f32 v37, v28, v45, v44
	ds_read_b128 v[28:31], v156 offset:4608
	ds_read_b128 v[32:35], v156 offset:4672
	s_waitcnt lgkmcnt(1)
	v_mfma_f32_16x16x32_bf16 v[28:31], v[28:31], v[24:27], 0
	s_waitcnt lgkmcnt(0)
	v_mfma_f32_16x16x32_bf16 v[28:31], v[32:35], v[20:23], v[28:31]
	v_add_f32_e32 v32, 0xc2000000, v36
	s_nop 6
	v_fma_f32 v58, v52, |v32|, v28
	v_add_f32_e32 v28, 0xc2040000, v36
	v_fma_f32 v57, v52, |v28|, v29
	v_add_f32_e32 v29, 0xc2080000, v36
	v_fma_f32 v56, v52, |v29|, v30
	v_add_f32_e32 v29, 0xc20c0000, v36
	v_max3_f32 v28, v37, v58, v57
	v_fma_f32 v55, v52, |v29|, v31
	v_max3_f32 v37, v28, v56, v55
	ds_read_b128 v[28:31], v157
	ds_read_b128 v[32:35], v157 offset:64
	s_waitcnt lgkmcnt(1)
	v_mfma_f32_16x16x32_bf16 v[28:31], v[28:31], v[24:27], 0
	s_waitcnt lgkmcnt(0)
	v_mfma_f32_16x16x32_bf16 v[28:31], v[32:35], v[20:23], v[28:31]
	v_add_f32_e32 v32, 0xc2400000, v36
	s_nop 6
	v_fma_f32 v62, v52, |v32|, v28
	v_add_f32_e32 v28, 0xc2440000, v36
	v_fma_f32 v61, v52, |v28|, v29
	v_add_f32_e32 v29, 0xc2480000, v36
	v_fma_f32 v60, v52, |v29|, v30
	v_add_f32_e32 v29, 0xc24c0000, v36
	v_max3_f32 v28, v37, v62, v61
	v_fma_f32 v59, v52, |v29|, v31
	v_max3_f32 v36, v28, v60, v59
	ds_read_b128 v[28:31], v156 offset:9216
	ds_read_b128 v[32:35], v156 offset:9280
	s_waitcnt lgkmcnt(1)
	v_mfma_f32_16x16x32_bf16 v[28:31], v[28:31], v[24:27], 0
	s_waitcnt lgkmcnt(0)
	v_mfma_f32_16x16x32_bf16 v[28:31], v[32:35], v[20:23], v[28:31]
	v_cndmask_b32_e64 v32, v134, v240, s[66:67]
	v_add_f32_e32 v33, 0xc2800000, v32
	s_nop 5
	v_fma_f32 v82, v52, |v33|, v28
	v_add_f32_e32 v28, 0xc2820000, v32
	v_fma_f32 v81, v52, |v28|, v29
	v_add_f32_e32 v29, 0xc2840000, v32
	v_fma_f32 v80, v52, |v29|, v30
	v_add_f32_e32 v29, 0xc2860000, v32
	v_max3_f32 v28, v36, v82, v81
	v_fma_f32 v63, v52, |v29|, v31
	v_max3_f32 v36, v28, v80, v63
	ds_read_b128 v[28:31], v156 offset:11520
	ds_read_b128 v[32:35], v156 offset:11584
	s_waitcnt lgkmcnt(1)
	v_mfma_f32_16x16x32_bf16 v[28:31], v[28:31], v[24:27], 0
	s_waitcnt lgkmcnt(0)
	v_mfma_f32_16x16x32_bf16 v[28:31], v[32:35], v[20:23], v[28:31]
	v_cndmask_b32_e64 v32, v134, v240, s[70:71]
	v_add_f32_e32 v33, 0xc2a00000, v32
	s_nop 5
	v_fma_f32 v165, v52, |v33|, v28
	v_add_f32_e32 v28, 0xc2a20000, v32
	v_fma_f32 v164, v52, |v28|, v29
	v_add_f32_e32 v29, 0xc2a40000, v32
	v_fma_f32 v163, v52, |v29|, v30
	v_add_f32_e32 v29, 0xc2a60000, v32
	v_max3_f32 v28, v36, v165, v164
	v_fma_f32 v83, v52, |v29|, v31
	v_max3_f32 v36, v28, v163, v83
	ds_read_b128 v[28:31], v156 offset:13824
	ds_read_b128 v[32:35], v156 offset:13888
	s_waitcnt lgkmcnt(1)
	v_mfma_f32_16x16x32_bf16 v[28:31], v[28:31], v[24:27], 0
	s_waitcnt lgkmcnt(0)
	v_mfma_f32_16x16x32_bf16 v[28:31], v[32:35], v[20:23], v[28:31]
	v_cndmask_b32_e64 v32, v134, v240, s[72:73]
	v_add_f32_e32 v33, 0xc2c00000, v32
	s_nop 5
	v_fma_f32 v169, v52, |v33|, v28
	v_add_f32_e32 v28, 0xc2c20000, v32
	v_fma_f32 v168, v52, |v28|, v29
	v_add_f32_e32 v29, 0xc2c40000, v32
	v_fma_f32 v167, v52, |v29|, v30
	v_add_f32_e32 v29, 0xc2c60000, v32
	v_max3_f32 v28, v36, v169, v168
	v_fma_f32 v166, v52, |v29|, v31
	v_max3_f32 v36, v28, v167, v166
	ds_read_b128 v[28:31], v158
	ds_read_b128 v[32:35], v158 offset:64
	s_waitcnt lgkmcnt(1)
	v_mfma_f32_16x16x32_bf16 v[28:31], v[28:31], v[24:27], 0
	s_waitcnt lgkmcnt(0)
	v_mfma_f32_16x16x32_bf16 v[28:31], v[32:35], v[20:23], v[28:31]
	v_cndmask_b32_e64 v32, v134, v240, s[74:75]
	v_add_f32_e32 v33, 0xc2e00000, v32
	s_nop 5
	v_fma_f32 v173, v52, |v33|, v28
	v_add_f32_e32 v28, 0xc2e20000, v32
	v_fma_f32 v172, v52, |v28|, v29
	v_add_f32_e32 v29, 0xc2e40000, v32
	v_fma_f32 v171, v52, |v29|, v30
	v_add_f32_e32 v29, 0xc2e60000, v32
	v_max3_f32 v28, v36, v173, v172
	v_fma_f32 v170, v52, |v29|, v31
	v_max3_f32 v36, v28, v171, v170
	ds_read_b128 v[28:31], v156 offset:18432
	ds_read_b128 v[32:35], v156 offset:18496
	s_waitcnt lgkmcnt(1)
	v_mfma_f32_16x16x32_bf16 v[28:31], v[28:31], v[24:27], 0
	s_waitcnt lgkmcnt(0)
	v_mfma_f32_16x16x32_bf16 v[28:31], v[32:35], v[20:23], v[28:31]
	s_nop 7
	v_fma_f32 v175, v52, v135, v28
	v_fma_f32 v29, v52, v136, v29
	v_max3_f32 v32, v36, v175, v29
	v_fma_f32 v28, v52, v137, v30
	v_fmac_f32_e32 v31, v52, v138
	v_max3_f32 v30, v32, v28, v31
	ds_read_b128 v[32:35], v156 offset:20736
	ds_read_b128 v[36:39], v156 offset:20800
	s_waitcnt lgkmcnt(1)
	v_mfma_f32_16x16x32_bf16 v[32:35], v[32:35], v[24:27], 0
	s_waitcnt lgkmcnt(0)
	v_mfma_f32_16x16x32_bf16 v[32:35], v[36:39], v[20:23], v[32:35]
	ds_read_b128 v[36:39], v156 offset:23040
	s_waitcnt lgkmcnt(0)
	v_mfma_f32_16x16x32_bf16 v[36:39], v[36:39], v[24:27], 0
	s_nop 4
	v_fma_f32 v181, v52, v139, v32
	v_fma_f32 v32, v52, v140, v33
	v_max3_f32 v33, v30, v181, v32
	v_mfma_f32_16x16x32_bf16 v[36:39], v[176:179], v[20:23], v[36:39]
	ds_read_b128 v[176:179], v159
	v_fma_f32 v30, v52, v141, v34
	v_fmac_f32_e32 v35, v52, v142
	s_waitcnt lgkmcnt(0)
	v_mfma_f32_16x16x32_bf16 v[24:27], v[176:179], v[24:27], 0
	ds_read_b128 v[176:179], v159 offset:64
	v_max3_f32 v33, v33, v30, v35
	s_nop 0
	v_fma_f32 v183, v52, v143, v36
	s_waitcnt lgkmcnt(0)
	v_mfma_f32_16x16x32_bf16 v[20:23], v[176:179], v[20:23], v[24:27]
	v_fma_f32 v184, v52, v144, v37
	v_max3_f32 v33, v33, v183, v184
	v_fma_f32 v185, v52, v145, v38
	v_fmac_f32_e32 v39, v52, v146
	v_max3_f32 v33, v33, v185, v39
	s_nop 2
	v_fma_f32 v20, v52, |v147|, v20
	v_fma_f32 v21, v52, |v148|, v21
	v_max3_f32 v24, v33, v20, v21
	v_fma_f32 v22, v52, |v149|, v22
	v_fma_f32 v23, v52, |v150|, v23
	v_max3_f32 v24, v24, v22, v23
	ds_bpermute_b32 v25, v53, v24
	s_waitcnt lgkmcnt(0)
	v_max_f32_e32 v25, v25, v25
	v_max_f32_e32 v24, v24, v25
	ds_bpermute_b32 v25, v54, v24
	s_waitcnt lgkmcnt(0)
	v_max_f32_e32 v25, v25, v25
	v_max_f32_e32 v24, v24, v25
	v_sub_f32_e32 v25, v43, v24
	v_exp_f32_e32 v186, v25
	v_sub_f32_e32 v26, v42, v24
	v_exp_f32_e32 v187, v26
	v_sub_f32_e32 v26, v41, v24
	v_exp_f32_e32 v188, v26
	v_sub_f32_e32 v26, v40, v24
	v_exp_f32_e32 v189, v26
	v_sub_f32_e32 v26, v47, v24
	v_add_f32_e32 v25, 0, v186
	v_exp_f32_e32 v190, v26
	v_sub_f32_e32 v26, v46, v24
	v_add_f32_e32 v25, v187, v25
	v_exp_f32_e32 v191, v26
	v_sub_f32_e32 v26, v45, v24
	v_add_f32_e32 v25, v188, v25
	v_exp_f32_e32 v192, v26
	v_sub_f32_e32 v26, v44, v24
	v_add_f32_e32 v25, v189, v25
	v_exp_f32_e32 v193, v26
	v_sub_f32_e32 v26, v58, v24
	v_add_f32_e32 v25, v190, v25
	v_exp_f32_e32 v174, v26
	v_sub_f32_e32 v26, v57, v24
	v_add_f32_e32 v25, v191, v25
	v_exp_f32_e32 v176, v26
	v_sub_f32_e32 v26, v56, v24
	v_add_f32_e32 v25, v192, v25
	v_exp_f32_e32 v177, v26
	v_sub_f32_e32 v26, v55, v24
	v_add_f32_e32 v25, v193, v25
	v_exp_f32_e32 v178, v26
	v_sub_f32_e32 v26, v62, v24
	v_add_f32_e32 v25, v174, v25
	v_exp_f32_e32 v179, v26
	v_sub_f32_e32 v26, v61, v24
	v_add_f32_e32 v25, v176, v25
	v_exp_f32_e32 v180, v26
	v_sub_f32_e32 v26, v60, v24
	v_add_f32_e32 v25, v177, v25
	v_exp_f32_e32 v182, v26
	v_sub_f32_e32 v26, v59, v24
	v_add_f32_e32 v25, v178, v25
	v_exp_f32_e32 v194, v26
	v_sub_f32_e32 v26, v82, v24
	v_add_f32_e32 v25, v179, v25
	v_exp_f32_e32 v56, v26
	v_sub_f32_e32 v26, v81, v24
	v_add_f32_e32 v25, v180, v25
	v_exp_f32_e32 v57, v26
	v_sub_f32_e32 v26, v80, v24
	v_add_f32_e32 v25, v182, v25
	v_exp_f32_e32 v58, v26
	v_sub_f32_e32 v26, v63, v24
	v_add_f32_e32 v25, v194, v25
	v_exp_f32_e32 v59, v26
	v_sub_f32_e32 v26, v165, v24
	v_add_f32_e32 v25, v56, v25
	v_exp_f32_e32 v60, v26
	v_sub_f32_e32 v26, v164, v24
	v_add_f32_e32 v25, v57, v25
	v_exp_f32_e32 v61, v26
	v_sub_f32_e32 v26, v163, v24
	v_add_f32_e32 v25, v58, v25
	v_exp_f32_e32 v62, v26
	v_sub_f32_e32 v26, v83, v24
	v_add_f32_e32 v25, v59, v25
	v_exp_f32_e32 v63, v26
	v_sub_f32_e32 v26, v169, v24
	v_add_f32_e32 v25, v60, v25
	v_exp_f32_e32 v42, v26
	v_sub_f32_e32 v26, v168, v24
	v_add_f32_e32 v25, v61, v25
	v_exp_f32_e32 v43, v26
	v_sub_f32_e32 v26, v167, v24
	v_add_f32_e32 v25, v62, v25
	v_exp_f32_e32 v44, v26
	v_sub_f32_e32 v26, v166, v24
	v_add_f32_e32 v25, v63, v25
	v_exp_f32_e32 v45, v26
	v_sub_f32_e32 v26, v173, v24
	v_add_f32_e32 v25, v42, v25
	v_exp_f32_e32 v46, v26
	v_sub_f32_e32 v26, v172, v24
	v_add_f32_e32 v25, v43, v25
	v_exp_f32_e32 v47, v26
	v_sub_f32_e32 v26, v171, v24
	v_add_f32_e32 v25, v44, v25
	v_exp_f32_e32 v52, v26
	v_sub_f32_e32 v26, v170, v24
	v_add_f32_e32 v25, v45, v25
	v_exp_f32_e32 v55, v26
	v_sub_f32_e32 v26, v175, v24
	v_add_f32_e32 v25, v46, v25
	v_exp_f32_e32 v33, v26
	v_sub_f32_e32 v26, v29, v24
	v_add_f32_e32 v25, v47, v25
	v_exp_f32_e32 v34, v26
	v_sub_f32_e32 v26, v28, v24
	v_add_f32_e32 v25, v52, v25
	v_exp_f32_e32 v36, v26
	v_sub_f32_e32 v26, v31, v24
	v_add_f32_e32 v25, v55, v25
	v_exp_f32_e32 v37, v26
	v_sub_f32_e32 v26, v181, v24
	v_add_f32_e32 v25, v33, v25
	v_exp_f32_e32 v38, v26
	v_sub_f32_e32 v26, v32, v24
	v_add_f32_e32 v25, v34, v25
	v_exp_f32_e32 v40, v26
	v_sub_f32_e32 v26, v30, v24
	v_add_f32_e32 v25, v36, v25
	v_exp_f32_e32 v41, v26
	v_sub_f32_e32 v26, v35, v24
	v_add_f32_e32 v25, v37, v25
	v_exp_f32_e32 v35, v26
	v_add_f32_e32 v25, v38, v25
	v_add_f32_e32 v25, v40, v25
	v_add_f32_e32 v25, v41, v25
	v_add_f32_e32 v26, v35, v25
	v_sub_f32_e32 v25, v183, v24
	v_exp_f32_e32 v25, v25
	v_sub_f32_e32 v20, v20, v24
	v_sub_f32_e32 v21, v21, v24
	ds_read2_b64 v[80:83], v51 offset0:128 offset1:132
	v_add_f32_e32 v27, v25, v26
	v_sub_f32_e32 v26, v184, v24
	v_exp_f32_e32 v26, v26
	v_cvt_pk_bf16_f32 v172, v174, v176
	v_cvt_pk_bf16_f32 v173, v177, v178
	v_cvt_pk_bf16_f32 v174, v179, v180
	v_add_f32_e32 v28, v26, v27
	v_sub_f32_e32 v27, v185, v24
	v_exp_f32_e32 v27, v27
	ds_read2_b64 v[176:179], v51 offset0:136 offset1:140
	v_sub_f32_e32 v1, v1, v24
	v_cvt_pk_bf16_f32 v56, v56, v57
	v_add_f32_e32 v29, v27, v28
	v_sub_f32_e32 v28, v39, v24
	v_exp_f32_e32 v28, v28
	v_cvt_pk_bf16_f32 v57, v58, v59
	v_cvt_pk_bf16_f32 v58, v60, v61
	v_cvt_pk_bf16_f32 v59, v62, v63
	v_add_f32_e32 v30, v28, v29
	v_exp_f32_e32 v29, v20
	ds_read2_b64 v[60:63], v51 offset0:144 offset1:148
	ds_read2_b64 v[164:167], v50 offset0:160 offset1:164
	v_cvt_pk_bf16_f32 v175, v182, v194
	v_add_f32_e32 v20, v29, v30
	v_exp_f32_e32 v30, v21
	v_sub_f32_e32 v21, v22, v24
	v_exp_f32_e32 v31, v21
	v_sub_f32_e32 v21, v23, v24
	v_exp_f32_e32 v32, v21
	v_add_f32_e32 v20, v30, v20
	v_add_f32_e32 v20, v31, v20
	v_cvt_pk_bf16_f32 v22, v190, v191
	v_add_f32_e32 v20, v32, v20
	ds_bpermute_b32 v21, v53, v20
	v_cvt_pk_bf16_f32 v23, v192, v193
	ds_read2_b64 v[168:171], v49 offset0:192 offset1:196
	v_cvt_pk_bf16_f32 v42, v42, v43
	v_cvt_pk_bf16_f32 v43, v44, v45
	s_waitcnt lgkmcnt(1)
	v_add_f32_e32 v20, v20, v21
	ds_bpermute_b32 v21, v54, v20
	v_cvt_pk_bf16_f32 v45, v52, v55
	ds_read2_b64 v[52:55], v51 offset0:152 offset1:156
	v_cvt_pk_bf16_f32 v44, v46, v47
	v_cvt_pk_bf16_f32 v27, v27, v28
	s_waitcnt lgkmcnt(1)
	v_add_f32_e32 v24, v20, v21
	v_cvt_pk_bf16_f32 v20, v186, v187
	v_cvt_pk_bf16_f32 v21, v188, v189
	ds_read2_b64 v[184:187], v48 offset0:128 offset1:132
	v_cvt_pk_bf16_f32 v28, v29, v30
	v_mfma_f32_16x16x32_bf16 v[80:83], v[80:83], v[20:23], 0
	v_cvt_pk_bf16_f32 v29, v31, v32
	v_cvt_pk_bf16_f32 v26, v25, v26
	v_exp_f32_e32 v1, v1
	v_mfma_f32_16x16x32_bf16 v[80:83], v[176:179], v[172:175], v[80:83]
	ds_read2_b64 v[176:179], v50 offset0:168 offset1:172
	v_add_f32_e32 v1, v1, v24
	v_mfma_f32_16x16x32_bf16 v[60:63], v[60:63], v[56:59], v[80:83]
	v_div_scale_f32 v24, s[6:7], v1, v1, 1.0
	v_rcp_f32_e32 v25, v24
	s_nop 2
	ds_read2_b64 v[80:83], v50 offset0:176 offset1:180
	v_mfma_f32_16x16x32_bf16 v[164:167], v[164:167], v[20:23], 0
	s_waitcnt lgkmcnt(1)
	v_mfma_f32_16x16x32_bf16 v[164:167], v[176:179], v[172:175], v[164:167]
	ds_read2_b64 v[176:179], v49 offset0:200 offset1:204
	s_waitcnt lgkmcnt(1)
	v_mfma_f32_16x16x32_bf16 v[80:83], v[80:83], v[56:59], v[164:167]
	v_mfma_f32_16x16x32_bf16 v[168:171], v[168:171], v[20:23], 0
	s_nop 3
	ds_read2_b64 v[164:167], v49 offset0:208 offset1:212
	s_waitcnt lgkmcnt(1)
	v_mfma_f32_16x16x32_bf16 v[168:171], v[176:179], v[172:175], v[168:171]
	ds_read2_b64 v[176:179], v48 offset0:136 offset1:140
	s_waitcnt lgkmcnt(1)
	v_mfma_f32_16x16x32_bf16 v[164:167], v[164:167], v[56:59], v[168:171]
	s_nop 4
	ds_read2_b64 v[168:171], v48 offset0:144 offset1:148
	v_mfma_f32_16x16x32_bf16 v[20:23], v[184:187], v[20:23], 0
	s_waitcnt lgkmcnt(1)
	v_mfma_f32_16x16x32_bf16 v[20:23], v[176:179], v[172:175], v[20:23]
	s_waitcnt lgkmcnt(0)
	v_mfma_f32_16x16x32_bf16 v[20:23], v[168:171], v[56:59], v[20:23]
	ds_read2_b64 v[56:59], v50 offset0:184 offset1:188
	v_mfma_f32_16x16x32_bf16 v[52:55], v[52:55], v[42:45], v[60:63]
	s_waitcnt lgkmcnt(0)
	v_mfma_f32_16x16x32_bf16 v[56:59], v[56:59], v[42:45], v[80:83]
	s_nop 0
	ds_read2_b64 v[60:63], v49 offset0:216 offset1:220
	s_nop 0
	ds_read2_b64 v[80:83], v48 offset0:152 offset1:156
	s_waitcnt lgkmcnt(1)
	v_mfma_f32_16x16x32_bf16 v[60:63], v[60:63], v[42:45], v[164:167]
	s_waitcnt lgkmcnt(0)
	v_mfma_f32_16x16x32_bf16 v[20:23], v[80:83], v[42:45], v[20:23]
	v_cvt_pk_bf16_f32 v42, v33, v34
	v_cvt_pk_bf16_f32 v43, v36, v37
	v_cvt_pk_bf16_f32 v45, v41, v35
	ds_read2_b64 v[34:37], v51 offset0:160 offset1:164
	v_cvt_pk_bf16_f32 v44, v38, v40
	ds_read2_b64 v[38:41], v50 offset0:192 offset1:196
	ds_read2_b64 v[30:33], v51 offset0:168 offset1:172
	s_waitcnt lgkmcnt(2)
	v_mfma_f32_16x16x32_bf16 v[34:37], v[34:37], v[42:45], v[52:55]
	s_nop 2
	ds_read2_b64 v[52:55], v49 offset0:224 offset1:228
	s_waitcnt lgkmcnt(2)
	v_mfma_f32_16x16x32_bf16 v[38:41], v[38:41], v[42:45], v[56:59]
	s_nop 2
	ds_read2_b64 v[56:59], v48 offset0:160 offset1:164
	s_waitcnt lgkmcnt(2)
	v_mfma_f32_16x16x32_bf16 v[30:33], v[30:33], v[26:29], v[34:37]
	s_nop 2
	ds_read2_b64 v[34:37], v50 offset0:200 offset1:204
	s_waitcnt lgkmcnt(2)
	v_mfma_f32_16x16x32_bf16 v[52:55], v[52:55], v[42:45], v[60:63]
	s_waitcnt lgkmcnt(1)
	v_mfma_f32_16x16x32_bf16 v[20:23], v[56:59], v[42:45], v[20:23]
	ds_read2_b64 v[42:45], v48 offset0:168 offset1:172
	s_waitcnt lgkmcnt(1)
	v_mfma_f32_16x16x32_bf16 v[34:37], v[34:37], v[26:29], v[38:41]
	s_nop 2
	ds_read2_b64 v[38:41], v49 offset0:232 offset1:236
	s_waitcnt lgkmcnt(0)
	v_mfma_f32_16x16x32_bf16 v[38:41], v[38:41], v[26:29], v[52:55]
	v_mfma_f32_16x16x32_bf16 v[20:23], v[42:45], v[26:29], v[20:23]
	v_fma_f32 v26, -v24, v25, 1.0
	v_fmac_f32_e32 v25, v26, v25
	v_div_scale_f32 v26, vcc, 1.0, v1, 1.0
	v_mul_f32_e32 v27, v26, v25
	v_fma_f32 v28, -v24, v27, v26
	v_fmac_f32_e32 v27, v28, v25
	v_fma_f32 v24, -v24, v27, v26
	v_div_fmas_f32 v24, v24, v25, v27
	v_or_b32_e32 v26, s2, v99
	v_mov_b32_e32 v27, v0
	v_div_fixup_f32 v24, v24, v1, 1.0
	v_lshlrev_b64 v[26:27], 11, v[26:27]
	v_lshl_add_u64 v[2:3], v[2:3], 0, v[26:27]
	v_pk_mul_f32 v[26:27], v[24:25], v[30:31] op_sel_hi:[0,1]
	v_pk_mul_f32 v[28:29], v[24:25], v[32:33] op_sel_hi:[0,1]
	v_cvt_pk_bf16_f32 v26, v26, v27
	v_cvt_pk_bf16_f32 v27, v28, v29
	ds_write_b64 v220, v[26:27]
	v_pk_mul_f32 v[26:27], v[24:25], v[34:35] op_sel_hi:[0,1]
	v_pk_mul_f32 v[28:29], v[24:25], v[36:37] op_sel_hi:[0,1]
	v_cvt_pk_bf16_f32 v26, v26, v27
	v_cvt_pk_bf16_f32 v27, v28, v29
	ds_write_b64 v220, v[26:27] offset:32
	v_pk_mul_f32 v[26:27], v[24:25], v[38:39] op_sel_hi:[0,1]
	v_pk_mul_f32 v[28:29], v[24:25], v[40:41] op_sel_hi:[0,1]
	v_pk_mul_f32 v[20:21], v[24:25], v[20:21] op_sel_hi:[0,1]
	v_pk_mul_f32 v[22:23], v[24:25], v[22:23] op_sel_hi:[0,1]
	v_cvt_pk_bf16_f32 v26, v26, v27
	v_cvt_pk_bf16_f32 v27, v28, v29
	v_cvt_pk_bf16_f32 v20, v20, v21
	v_cvt_pk_bf16_f32 v21, v22, v23
	ds_write_b64 v220, v[26:27] offset:64
	ds_write_b64 v220, v[20:21] offset:96
	s_waitcnt lgkmcnt(0)
	ds_read_b128 v[226:229], v221
	ds_read_b128 v[230:233], v221 offset:1152
	s_mov_b32 s98, 0x18000
	s_mov_b32 s99, 0
	v_lshl_add_u64 v[224:225], v[222:223], 0, s[98:99]
	s_waitcnt lgkmcnt(1)
	global_store_dwordx4 v[224:225], v[226:229], off sc1
	s_mov_b32 s98, 0x1c000
	v_lshl_add_u64 v[224:225], v[222:223], 0, s[98:99]
	s_waitcnt lgkmcnt(0)
	global_store_dwordx4 v[224:225], v[230:233], off sc1
	s_branch .LBB0_755

	.amdhsa_kernel _Z8yoco_fwd6Params
		.amdhsa_group_segment_fixed_size 0
		.amdhsa_private_segment_fixed_size 0
		.amdhsa_kernarg_size 424
		.amdhsa_user_sgpr_count 2
		.amdhsa_user_sgpr_dispatch_ptr 0
		.amdhsa_user_sgpr_queue_ptr 0
		.amdhsa_user_sgpr_kernarg_segment_ptr 1
		.amdhsa_user_sgpr_dispatch_id 0
		.amdhsa_user_sgpr_kernarg_preload_length 0
		.amdhsa_user_sgpr_kernarg_preload_offset 0
		.amdhsa_user_sgpr_private_segment_size 0
		.amdhsa_uses_dynamic_stack 0
		.amdhsa_enable_private_segment 0
		.amdhsa_system_sgpr_workgroup_id_x 1
		.amdhsa_system_sgpr_workgroup_id_y 0
		.amdhsa_system_sgpr_workgroup_id_z 0
		.amdhsa_system_sgpr_workgroup_info 0
		.amdhsa_system_vgpr_workitem_id 2
		.amdhsa_next_free_vgpr 256
		.amdhsa_next_free_sgpr 102
		.amdhsa_accum_offset 256
		.amdhsa_reserve_vcc 1
		.amdhsa_float_round_mode_32 0
		.amdhsa_float_round_mode_16_64 0
		.amdhsa_float_denorm_mode_32 3
		.amdhsa_float_denorm_mode_16_64 3
		.amdhsa_dx10_clamp 1
		.amdhsa_ieee_mode 1
		.amdhsa_fp16_overflow 0
		.amdhsa_tg_split 0
		.amdhsa_exception_fp_ieee_invalid_op 0
		.amdhsa_exception_fp_denorm_src 0
		.amdhsa_exception_fp_ieee_div_zero 0
		.amdhsa_exception_fp_ieee_overflow 0
		.amdhsa_exception_fp_ieee_underflow 0
		.amdhsa_exception_fp_ieee_inexact 0
		.amdhsa_exception_int_div_zero 0
	.end_amdhsa_kernel

amdhsa.kernels:
  - .agpr_count:     0
    .args:
      - .offset:         0
        .size:           168
        .value_kind:     by_value
      - .offset:         168
        .size:           4
        .value_kind:     hidden_block_count_x
      - .offset:         172
        .size:           4
        .value_kind:     hidden_block_count_y
      - .offset:         176
        .size:           4
        .value_kind:     hidden_block_count_z
      - .offset:         180
        .size:           2
        .value_kind:     hidden_group_size_x
      - .offset:         182
        .size:           2
        .value_kind:     hidden_group_size_y
      - .offset:         184
        .size:           2
        .value_kind:     hidden_group_size_z
      - .offset:         186
        .size:           2
        .value_kind:     hidden_remainder_x
      - .offset:         188
        .size:           2
        .value_kind:     hidden_remainder_y
      - .offset:         190
        .size:           2
        .value_kind:     hidden_remainder_z
      - .offset:         208
        .size:           8
        .value_kind:     hidden_global_offset_x
      - .offset:         216
        .size:           8
        .value_kind:     hidden_global_offset_y
      - .offset:         224
        .size:           8
        .value_kind:     hidden_global_offset_z
      - .offset:         232
        .size:           2
        .value_kind:     hidden_grid_dims
      - .offset:         256
        .size:           8
        .value_kind:     hidden_multigrid_sync_arg
      - .offset:         288
        .size:           4
        .value_kind:     hidden_dynamic_lds_size
    .group_segment_fixed_size: 0
    .kernarg_segment_align: 8
    .kernarg_segment_size: 424
    .language:       OpenCL C
    .language_version:
      - 2
      - 0
    .max_flat_workgroup_size: 512
    .name:           _Z8yoco_fwd6Params
    .private_segment_fixed_size: 0
    .sgpr_count:     108
    .sgpr_spill_count: 206
    .symbol:         _Z8yoco_fwd6Params.kd
    .uniform_work_group_size: 1
    .uses_dynamic_stack: false
    .vgpr_count:     256
    .vgpr_spill_count: 0
    .wavefront_size: 64
